# fast_gemm RESID epilogue: 4 row-chunk loads batched per row group with counted vmcnt(3) (was load-wait-fma-store x32 serialized) + LRU tile loads batched + attn
# speedup vs baseline: 1.1118x; 1.0155x over previous
;   __device__ __forceinline__ void operator()(const f32x4 (&acc)[2][2][4][2], const pg8::Unit& u, int wr, int wc, int fr, int fq) const {
;     ...
;           float* xb;
;           { int b_ = row >= TPB ? 1 : 0; int u_ = row - b_ * TPB;
;             xb = (u_ < CTX) ? xctx + (size_t)(b_ * CTX + u_) * D : xout + ((size_t)b_ * SEQ + (u_ - CTX)) * D; }
;           const float* xr = (xb >= xout && xb < xout + (size_t)2 * SEQ * D) ? xin + (xb - xout) : xb;
; #pragma unroll
;           for (int bj = 0; bj < 2; ++bj)
; #pragma unroll
;             for (int n = 0; n < 2; ++n) {
;               int cc = u.pn * 256 + bj * 128 + wc * 32 + n * 16 + fq * 4;
;               const float4 gs = gsv[bj][n];
;               float4 xv = *(const float4*)(xr + cc);
;               f32x4 a = acc[ai][bj][m][n];
;               xv.x += gs.x * a[0]; xv.y += gs.y * a[1]; xv.z += gs.z * a[2]; xv.w += gs.w * a[3];
;               *(float4*)(xb + cc) = xv;
;             }
.LBB0_339:
	s_or_b64 exec, exec, s[4:5]
	v_lshlrev_b64 v[16:17], 12, v[16:17]
	v_lshl_add_u64 v[16:17], v[18:19], 0, v[16:17]
	v_cmp_le_u64_e32 vcc, s[44:45], v[16:17]
	v_cmp_gt_u64_e64 s[42:43], s[56:57], v[16:17]
	s_and_b64 vcc, vcc, s[42:43]
	v_subrev_co_u32_e64 v18, s[42:43], s44, v16
	v_mov_b32_e32 v19, s45
	s_nop 0
	v_subb_co_u32_e64 v19, s[42:43], v17, v19, s[42:43]
	v_lshl_add_u64 v[18:19], s[44:45], 0, v[18:19]
	v_cndmask_b32_e32 v19, v17, v19, vcc
	v_cndmask_b32_e32 v18, v16, v18, vcc
	v_lshl_add_u64 v[20:21], v[18:19], 0, v[152:153]
	v_lshl_add_u64 v[22:23], v[16:17], 0, v[152:153]
	global_load_dwordx4 v[16:19], v[20:21], off
	global_load_dwordx4 v[180:183], v[20:21], off offset:64
	global_load_dwordx4 v[184:187], v[20:21], off offset:512
	global_load_dwordx4 v[188:191], v[20:21], off offset:576
	s_and_b64 vcc, exec, s[40:41]
	s_mov_b32 s4, s58
	s_mov_b32 s42, s60
	s_mov_b64 s[8:9], s[64:65]
	s_mov_b64 s[6:7], s[62:63]
	s_waitcnt vmcnt(3)
	v_pk_fma_f32 v[12:13], v[12:13], v[96:97], v[16:17]
	v_pk_fma_f32 v[14:15], v[14:15], v[98:99], v[18:19]
	global_store_dwordx4 v[22:23], v[12:15], off
	s_waitcnt vmcnt(3)
	v_pk_fma_f32 v[8:9], v[8:9], v[88:89], v[180:181]
	v_pk_fma_f32 v[10:11], v[10:11], v[90:91], v[182:183]
	global_store_dwordx4 v[22:23], v[8:11], off offset:64
	s_waitcnt vmcnt(3)
	v_pk_fma_f32 v[4:5], v[4:5], v[84:85], v[184:185]
	v_pk_fma_f32 v[6:7], v[6:7], v[86:87], v[186:187]
	global_store_dwordx4 v[22:23], v[4:7], off offset:512
	s_waitcnt vmcnt(3)
	v_pk_fma_f32 v[0:1], v[0:1], v[80:81], v[188:189]
	v_pk_fma_f32 v[2:3], v[2:3], v[82:83], v[190:191]
	global_store_dwordx4 v[22:23], v[0:3], off offset:576
	s_cbranch_vccnz .LBB0_380

; #define PG8_STAGE(bufoff, gbase, voff) do { _Pragma("unroll") for (int _i = 0; _i < 2; ++_i) \
;         __builtin_amdgcn_global_load_lds((const unsigned*)((const char*)(gbase) + (voff)[_i]), (PG8_LAS unsigned*)(lds + (bufoff) + ldsw + _i * 8192), 16, 0, 0); } while (0)
; #define PG8_LDA(dst, b, h) do { _Pragma("unroll") for (int m = 0; m < 4; ++m) _Pragma("unroll") for (int k = 0; k < 2; ++k) dst[m][k] = *(const PG8_LAS bf16x8*)(lds + PG8_SA(b, h) + aoff + m * 2048 + k * 1024); } while (0)
; #define PG8_LDB(dst, b, h) do { _Pragma("unroll") for (int n = 0; n < 2; ++n) _Pragma("unroll") for (int k = 0; k < 2; ++k) dst[n][k] = *(const PG8_LAS bf16x8*)(lds + PG8_SB(b, h) + boff + n * 2048 + k * 1024); } while (0)
; #define PG8_MMA(ai, bj, At, Bt) do { __builtin_amdgcn_s_setprio(1); _Pragma("unroll") for (int m = 0; m < 4; ++m) _Pragma("unroll") for (int n = 0; n < 2; ++n) _Pragma("unroll") for (int k = 0; k < 2; ++k) \
;         acc[ai][bj][m][n] = __builtin_amdgcn_mfma_f32_16x16x32_bf16(Bt[n][k], At[m][k], acc[ai][bj][m][n], 0, 0, 0); __builtin_amdgcn_s_setprio(0); } while (0)
; #define PG8_WAIT_V(n) asm volatile("s_waitcnt vmcnt(" #n ")" ::: "memory")
; #define PG8_WAIT_L(n) asm volatile("s_waitcnt lgkmcnt(" #n ")" ::: "memory")
; #define PG8_BAR __builtin_amdgcn_s_barrier()
; #define PG8_SCHED __builtin_amdgcn_sched_barrier(0)
; template <class Epi>
; __device__ __forceinline__ void gemm_phase(PG8_LAS unsigned char* lds, const Gemm g, const Sched& S, const Epi& E) {
;     ...
;             PG8_LDB(B0, 0, 0); PG8_SCHED; PG8_LDA(At, 0, 0); PG8_STAGE(PG8_SA(1, 1), a1 + hsA, voffA);
;             PG8_WAIT_L(8); PG8_BAR; PG8_WAIT_L(0); PG8_MMA(0, 0, At, B0); PG8_BAR; PG8_SCHED;
;             PG8_LDB(B1, 0, 1); PG8_STAGE(PG8_SB(0, 0), b2, voffB);
;             PG8_BAR; PG8_WAIT_L(0); PG8_MMA(0, 1, At, B1); PG8_BAR;
;             PG8_LDA(At, 0, 1); PG8_STAGE(PG8_SA(0, 0), a2, voffA);
;             PG8_BAR; PG8_WAIT_L(0); PG8_MMA(1, 0, At, B0); PG8_BAR; PG8_SCHED;
;             PG8_STAGE(PG8_SB(0, 1), b2 + hsB, voffB);
;             PG8_WAIT_V(6); PG8_BAR; PG8_MMA(1, 1, At, B1); PG8_BAR;
.LBB0_347:
	s_add_u32 s8, s6, 0xfffc0080
	s_addc_u32 s9, s7, -1
	s_add_i32 s39, 0, 0x10000
	v_add_u32_e32 v96, s39, v157
	ds_read_b128 v[80:83], v96
	ds_read_b128 v[84:87], v96 offset:1024
	ds_read_b128 v[88:91], v96 offset:2048
	ds_read_b128 v[96:99], v96 offset:3072
	s_cmp_eq_u32 s38, 12
	s_cselect_b32 s11, s2, s9
	s_cselect_b32 s10, s3, s8
	s_cselect_b32 s9, s5, s37
	s_cselect_b32 s8, s30, s36
	v_lshl_add_u64 v[202:203], s[6:7], 0, v[148:149]
	s_add_i32 m0, s15, 0xc000
	ds_read_b128 v[152:155], v162
	ds_read_b128 v[172:175], v162 offset:1024
	ds_read_b128 v[178:181], v162 offset:2048
	ds_read_b128 v[182:185], v162 offset:3072
	ds_read_b128 v[186:189], v162 offset:4096
	ds_read_b128 v[190:193], v162 offset:5120
	ds_read_b128 v[194:197], v162 offset:6144
	ds_read_b128 v[198:201], v162 offset:7168
	global_load_lds_dwordx4 v[202:203], off
	v_lshl_add_u64 v[202:203], s[6:7], 0, v[150:151]
	s_add_i32 m0, s15, 0xe000
	s_nop 0
	global_load_lds_dwordx4 v[202:203], off
	s_waitcnt lgkmcnt(8)
	s_barrier
	s_waitcnt lgkmcnt(0)
	s_setprio 1
	s_waitcnt lgkmcnt(0)
	v_mfma_f32_16x16x32_bf16 v[140:143], v[80:83], v[152:155], v[140:143]
	v_mfma_f32_16x16x32_bf16 v[136:139], v[88:91], v[152:155], v[136:139]
	v_mfma_f32_16x16x32_bf16 v[124:127], v[80:83], v[178:181], v[124:127]
	v_mfma_f32_16x16x32_bf16 v[120:123], v[88:91], v[178:181], v[120:123]
	v_mfma_f32_16x16x32_bf16 v[108:111], v[80:83], v[186:189], v[108:111]
	v_mfma_f32_16x16x32_bf16 v[104:107], v[88:91], v[186:189], v[104:107]
	v_mfma_f32_16x16x32_bf16 v[76:79], v[80:83], v[194:197], v[76:79]
	v_mfma_f32_16x16x32_bf16 v[72:75], v[88:91], v[194:197], v[72:75]
	v_mfma_f32_16x16x32_bf16 v[140:143], v[84:87], v[172:175], v[140:143]
	v_mfma_f32_16x16x32_bf16 v[136:139], v[96:99], v[172:175], v[136:139]
	v_mfma_f32_16x16x32_bf16 v[124:127], v[84:87], v[182:185], v[124:127]
	v_mfma_f32_16x16x32_bf16 v[120:123], v[96:99], v[182:185], v[120:123]
	v_mfma_f32_16x16x32_bf16 v[108:111], v[84:87], v[190:193], v[108:111]
	v_mfma_f32_16x16x32_bf16 v[104:107], v[96:99], v[190:193], v[104:107]
	v_mfma_f32_16x16x32_bf16 v[76:79], v[84:87], v[198:201], v[76:79]
	v_mfma_f32_16x16x32_bf16 v[72:75], v[96:99], v[198:201], v[72:75]
	s_setprio 0
	s_barrier
	s_add_i32 s43, 0, 0x14000
	s_add_i32 s39, s39, s14
	v_add_u32_e32 v166, s43, v157
	v_lshl_add_u64 v[214:215], s[8:9], 0, v[144:145]
	s_mov_b32 m0, s39
	ds_read_b128 v[202:205], v166
	ds_read_b128 v[206:209], v166 offset:1024
	ds_read_b128 v[210:213], v166 offset:2048
	ds_read_b128 v[236:239], v166 offset:3072
	global_load_lds_dwordx4 v[214:215], off
	v_lshl_add_u64 v[240:241], s[8:9], 0, v[146:147]
	s_add_i32 m0, s39, 0x2000
	s_nop 0
	global_load_lds_dwordx4 v[240:241], off
	s_barrier
	s_waitcnt lgkmcnt(0)
	s_setprio 1
	s_waitcnt lgkmcnt(0)
	v_mfma_f32_16x16x32_bf16 v[132:135], v[202:205], v[152:155], v[132:135]
	v_mfma_f32_16x16x32_bf16 v[128:131], v[210:213], v[152:155], v[128:131]
	v_mfma_f32_16x16x32_bf16 v[116:119], v[202:205], v[178:181], v[116:119]
	v_mfma_f32_16x16x32_bf16 v[112:115], v[210:213], v[178:181], v[112:115]
	v_mfma_f32_16x16x32_bf16 v[100:103], v[202:205], v[186:189], v[100:103]
	v_mfma_f32_16x16x32_bf16 v[92:95], v[210:213], v[186:189], v[92:95]
	v_mfma_f32_16x16x32_bf16 v[68:71], v[202:205], v[194:197], v[68:71]
	v_mfma_f32_16x16x32_bf16 v[64:67], v[210:213], v[194:197], v[64:67]
	v_mfma_f32_16x16x32_bf16 v[132:135], v[206:209], v[172:175], v[132:135]
	v_mfma_f32_16x16x32_bf16 v[128:131], v[236:239], v[172:175], v[128:131]
	v_mfma_f32_16x16x32_bf16 v[116:119], v[206:209], v[182:185], v[116:119]
	v_mfma_f32_16x16x32_bf16 v[112:115], v[236:239], v[182:185], v[112:115]
	v_mfma_f32_16x16x32_bf16 v[100:103], v[206:209], v[190:193], v[100:103]
	v_mfma_f32_16x16x32_bf16 v[92:95], v[236:239], v[190:193], v[92:95]
	v_mfma_f32_16x16x32_bf16 v[68:71], v[206:209], v[198:201], v[68:71]
	v_mfma_f32_16x16x32_bf16 v[64:67], v[236:239], v[198:201], v[64:67]
	s_setprio 0
	s_mov_b32 m0, s15
	v_lshl_add_u64 v[242:243], s[10:11], 0, v[144:145]
	s_barrier
	ds_read_b128 v[152:155], v162 offset:16384
	ds_read_b128 v[172:175], v162 offset:17408
	ds_read_b128 v[178:181], v162 offset:18432
	ds_read_b128 v[182:185], v162 offset:19456
	ds_read_b128 v[186:189], v162 offset:20480
	ds_read_b128 v[190:193], v162 offset:21504
	ds_read_b128 v[194:197], v162 offset:22528
	ds_read_b128 v[198:201], v162 offset:23552
	global_load_lds_dwordx4 v[242:243], off
	v_lshl_add_u64 v[244:245], s[10:11], 0, v[146:147]
	s_mov_b32 m0, s16
	s_nop 0
	global_load_lds_dwordx4 v[244:245], off
	s_barrier
	s_waitcnt lgkmcnt(0)
	s_setprio 1
	s_waitcnt lgkmcnt(0)
	v_mfma_f32_16x16x32_bf16 v[60:63], v[80:83], v[152:155], v[60:63]
	v_mfma_f32_16x16x32_bf16 v[56:59], v[88:91], v[152:155], v[56:59]
	v_mfma_f32_16x16x32_bf16 v[44:47], v[80:83], v[178:181], v[44:47]
	v_mfma_f32_16x16x32_bf16 v[40:43], v[88:91], v[178:181], v[40:43]
	v_mfma_f32_16x16x32_bf16 v[28:31], v[80:83], v[186:189], v[28:31]
	v_mfma_f32_16x16x32_bf16 v[24:27], v[88:91], v[186:189], v[24:27]
	v_mfma_f32_16x16x32_bf16 v[12:15], v[80:83], v[194:197], v[12:15]
	v_mfma_f32_16x16x32_bf16 v[8:11], v[88:91], v[194:197], v[8:11]
	v_mfma_f32_16x16x32_bf16 v[60:63], v[84:87], v[172:175], v[60:63]
	v_mfma_f32_16x16x32_bf16 v[56:59], v[96:99], v[172:175], v[56:59]
	v_mfma_f32_16x16x32_bf16 v[44:47], v[84:87], v[182:185], v[44:47]
	v_mfma_f32_16x16x32_bf16 v[40:43], v[96:99], v[182:185], v[40:43]
	v_mfma_f32_16x16x32_bf16 v[28:31], v[84:87], v[190:193], v[28:31]
	v_mfma_f32_16x16x32_bf16 v[24:27], v[96:99], v[190:193], v[24:27]
	v_mfma_f32_16x16x32_bf16 v[12:15], v[84:87], v[198:201], v[12:15]
	v_mfma_f32_16x16x32_bf16 v[8:11], v[96:99], v[198:201], v[8:11]
	s_setprio 0
	s_barrier
; #define PG8_STAGE(bufoff, gbase, voff) do { _Pragma("unroll") for (int _i = 0; _i < 2; ++_i) \
;         __builtin_amdgcn_global_load_lds((const unsigned*)((const char*)(gbase) + (voff)[_i]), (PG8_LAS unsigned*)(lds + (bufoff) + ldsw + _i * 8192), 16, 0, 0); } while (0)
; #define PG8_LDA(dst, b, h) do { _Pragma("unroll") for (int m = 0; m < 4; ++m) _Pragma("unroll") for (int k = 0; k < 2; ++k) dst[m][k] = *(const PG8_LAS bf16x8*)(lds + PG8_SA(b, h) + aoff + m * 2048 + k * 1024); } while (0)
; #define PG8_LDB(dst, b, h) do { _Pragma("unroll") for (int n = 0; n < 2; ++n) _Pragma("unroll") for (int k = 0; k < 2; ++k) dst[n][k] = *(const PG8_LAS bf16x8*)(lds + PG8_SB(b, h) + boff + n * 2048 + k * 1024); } while (0)
; #define PG8_MMA(ai, bj, At, Bt) do { __builtin_amdgcn_s_setprio(1); _Pragma("unroll") for (int m = 0; m < 4; ++m) _Pragma("unroll") for (int n = 0; n < 2; ++n) _Pragma("unroll") for (int k = 0; k < 2; ++k) \
;         acc[ai][bj][m][n] = __builtin_amdgcn_mfma_f32_16x16x32_bf16(Bt[n][k], At[m][k], acc[ai][bj][m][n], 0, 0, 0); __builtin_amdgcn_s_setprio(0); } while (0)
; #define PG8_WAIT_V(n) asm volatile("s_waitcnt vmcnt(" #n ")" ::: "memory")
; #define PG8_WAIT_L(n) asm volatile("s_waitcnt lgkmcnt(" #n ")" ::: "memory")
; #define PG8_BAR __builtin_amdgcn_s_barrier()
; #define PG8_SCHED __builtin_amdgcn_sched_barrier(0)
; template <class Epi>
; __device__ __forceinline__ void gemm_phase(PG8_LAS unsigned char* lds, const Gemm g, const Sched& S, const Epi& E) {
;     ...
;             PG8_WAIT_V(6); PG8_BAR; PG8_MMA(1, 1, At, B1); PG8_BAR;
;             PG8_LDB(B0, 1, 0); PG8_SCHED; PG8_LDA(At, 1, 0); PG8_STAGE(PG8_SA(0, 1), a2 + hsA, voffA);
;             PG8_WAIT_L(8); PG8_BAR; PG8_WAIT_L(0); PG8_MMA(0, 0, At, B0); PG8_BAR; PG8_SCHED;
;             PG8_LDB(B1, 1, 1); PG8_STAGE(PG8_SB(1, 0), b3, voffB);
;             PG8_BAR; PG8_WAIT_L(0); PG8_MMA(0, 1, At, B1); PG8_BAR;
;             PG8_LDA(At, 1, 1); PG8_STAGE(PG8_SA(1, 0), a3, voffA);
;             PG8_BAR; PG8_WAIT_L(0); PG8_MMA(1, 0, At, B0); PG8_BAR; PG8_SCHED;
	s_add_u32 s66, s8, 0x40000
	s_addc_u32 s67, s9, 0
	s_add_i32 s39, s43, s14
	v_lshl_add_u64 v[80:81], s[66:67], 0, v[144:145]
	s_mov_b32 m0, s39
	s_nop 0
	global_load_lds_dwordx4 v[80:81], off
	v_lshl_add_u64 v[80:81], s[66:67], 0, v[146:147]
	s_add_i32 m0, s39, 0x2000
	s_nop 0
	global_load_lds_dwordx4 v[80:81], off
	s_waitcnt vmcnt(6)
	s_barrier
	s_setprio 1
	v_mfma_f32_16x16x32_bf16 v[52:55], v[202:205], v[152:155], v[52:55]
	v_mfma_f32_16x16x32_bf16 v[48:51], v[210:213], v[152:155], v[48:51]
	v_mfma_f32_16x16x32_bf16 v[36:39], v[202:205], v[178:181], v[36:39]
	v_mfma_f32_16x16x32_bf16 v[32:35], v[210:213], v[178:181], v[32:35]
	v_mfma_f32_16x16x32_bf16 v[20:23], v[202:205], v[186:189], v[20:23]
	v_mfma_f32_16x16x32_bf16 v[16:19], v[210:213], v[186:189], v[16:19]
	v_mfma_f32_16x16x32_bf16 v[4:7], v[202:205], v[194:197], v[4:7]
	v_mfma_f32_16x16x32_bf16 v[0:3], v[210:213], v[194:197], v[0:3]
	v_mfma_f32_16x16x32_bf16 v[52:55], v[206:209], v[172:175], v[52:55]
	v_mfma_f32_16x16x32_bf16 v[48:51], v[236:239], v[172:175], v[48:51]
	v_mfma_f32_16x16x32_bf16 v[36:39], v[206:209], v[182:185], v[36:39]
	v_mfma_f32_16x16x32_bf16 v[32:35], v[236:239], v[182:185], v[32:35]
	v_mfma_f32_16x16x32_bf16 v[20:23], v[206:209], v[190:193], v[20:23]
	v_mfma_f32_16x16x32_bf16 v[16:19], v[236:239], v[190:193], v[16:19]
	v_mfma_f32_16x16x32_bf16 v[4:7], v[206:209], v[198:201], v[4:7]
	v_mfma_f32_16x16x32_bf16 v[0:3], v[236:239], v[198:201], v[0:3]
	s_setprio 0
	s_add_i32 s39, 0, 0x18000
	v_add_u32_e32 v96, s39, v157
	s_barrier
	ds_read_b128 v[80:83], v96
	ds_read_b128 v[84:87], v96 offset:1024
	ds_read_b128 v[88:91], v96 offset:2048
	ds_read_b128 v[96:99], v96 offset:3072
	s_add_u32 s10, s10, 0x40000
	s_addc_u32 s11, s11, 0
	s_mov_b32 m0, s17
	v_lshl_add_u64 v[202:203], s[10:11], 0, v[144:145]
	ds_read_b128 v[152:155], v162 offset:32768
	ds_read_b128 v[172:175], v162 offset:33792
	ds_read_b128 v[178:181], v162 offset:34816
	ds_read_b128 v[182:185], v162 offset:35840
	ds_read_b128 v[186:189], v162 offset:36864
	ds_read_b128 v[190:193], v162 offset:37888
	ds_read_b128 v[194:197], v162 offset:38912
	ds_read_b128 v[198:201], v162 offset:39936
	global_load_lds_dwordx4 v[202:203], off
	v_lshl_add_u64 v[202:203], s[10:11], 0, v[146:147]
	s_mov_b32 m0, s20
	s_nop 0
	global_load_lds_dwordx4 v[202:203], off
	s_waitcnt lgkmcnt(8)
	s_barrier
	s_waitcnt lgkmcnt(0)
	s_setprio 1
	s_waitcnt lgkmcnt(0)
	v_mfma_f32_16x16x32_bf16 v[140:143], v[80:83], v[152:155], v[140:143]
	v_mfma_f32_16x16x32_bf16 v[136:139], v[88:91], v[152:155], v[136:139]
	v_mfma_f32_16x16x32_bf16 v[124:127], v[80:83], v[178:181], v[124:127]
	v_mfma_f32_16x16x32_bf16 v[120:123], v[88:91], v[178:181], v[120:123]
	v_mfma_f32_16x16x32_bf16 v[108:111], v[80:83], v[186:189], v[108:111]
	v_mfma_f32_16x16x32_bf16 v[104:107], v[88:91], v[186:189], v[104:107]
	v_mfma_f32_16x16x32_bf16 v[76:79], v[80:83], v[194:197], v[76:79]
	v_mfma_f32_16x16x32_bf16 v[72:75], v[88:91], v[194:197], v[72:75]
	v_mfma_f32_16x16x32_bf16 v[140:143], v[84:87], v[172:175], v[140:143]
	v_mfma_f32_16x16x32_bf16 v[136:139], v[96:99], v[172:175], v[136:139]
	v_mfma_f32_16x16x32_bf16 v[124:127], v[84:87], v[182:185], v[124:127]
	v_mfma_f32_16x16x32_bf16 v[120:123], v[96:99], v[182:185], v[120:123]
	v_mfma_f32_16x16x32_bf16 v[108:111], v[84:87], v[190:193], v[108:111]
	v_mfma_f32_16x16x32_bf16 v[104:107], v[96:99], v[190:193], v[104:107]
	v_mfma_f32_16x16x32_bf16 v[76:79], v[84:87], v[198:201], v[76:79]
	v_mfma_f32_16x16x32_bf16 v[72:75], v[96:99], v[198:201], v[72:75]
	s_setprio 0
	s_barrier
	s_add_i32 s10, 0, 0x1c000
	s_add_i32 s11, s39, s14
	v_add_u32_e32 v166, s10, v157
	v_lshl_add_u64 v[214:215], v[214:215], 0, s[76:77]
	s_mov_b32 m0, s11
	ds_read_b128 v[202:205], v166
	ds_read_b128 v[206:209], v166 offset:1024
	ds_read_b128 v[210:213], v166 offset:2048
	ds_read_b128 v[236:239], v166 offset:3072
	global_load_lds_dwordx4 v[214:215], off
	v_lshl_add_u64 v[214:215], v[240:241], 0, s[76:77]
	s_add_i32 m0, s11, 0x2000
	s_nop 0
	global_load_lds_dwordx4 v[214:215], off
	s_barrier
	s_waitcnt lgkmcnt(0)
	s_setprio 1
	s_waitcnt lgkmcnt(0)
	v_mfma_f32_16x16x32_bf16 v[132:135], v[202:205], v[152:155], v[132:135]
	v_mfma_f32_16x16x32_bf16 v[128:131], v[210:213], v[152:155], v[128:131]
	v_mfma_f32_16x16x32_bf16 v[116:119], v[202:205], v[178:181], v[116:119]
	v_mfma_f32_16x16x32_bf16 v[112:115], v[210:213], v[178:181], v[112:115]
	v_mfma_f32_16x16x32_bf16 v[100:103], v[202:205], v[186:189], v[100:103]
	v_mfma_f32_16x16x32_bf16 v[92:95], v[210:213], v[186:189], v[92:95]
	v_mfma_f32_16x16x32_bf16 v[68:71], v[202:205], v[194:197], v[68:71]
	v_mfma_f32_16x16x32_bf16 v[64:67], v[210:213], v[194:197], v[64:67]
	v_mfma_f32_16x16x32_bf16 v[132:135], v[206:209], v[172:175], v[132:135]
	v_mfma_f32_16x16x32_bf16 v[128:131], v[236:239], v[172:175], v[128:131]
	v_mfma_f32_16x16x32_bf16 v[116:119], v[206:209], v[182:185], v[116:119]
	v_mfma_f32_16x16x32_bf16 v[112:115], v[236:239], v[182:185], v[112:115]
	v_mfma_f32_16x16x32_bf16 v[100:103], v[206:209], v[190:193], v[100:103]
	v_mfma_f32_16x16x32_bf16 v[92:95], v[236:239], v[190:193], v[92:95]
	v_mfma_f32_16x16x32_bf16 v[68:71], v[206:209], v[198:201], v[68:71]
	v_mfma_f32_16x16x32_bf16 v[64:67], v[236:239], v[198:201], v[64:67]
	s_setprio 0
	s_mov_b32 m0, s21
	v_lshl_add_u64 v[214:215], v[242:243], 0, s[76:77]
	s_barrier
	ds_read_b128 v[152:155], v162 offset:49152
	ds_read_b128 v[172:175], v162 offset:50176
	ds_read_b128 v[178:181], v162 offset:51200
	ds_read_b128 v[182:185], v162 offset:52224
	ds_read_b128 v[186:189], v162 offset:53248
	ds_read_b128 v[190:193], v162 offset:54272
	ds_read_b128 v[194:197], v162 offset:55296
	ds_read_b128 v[198:201], v162 offset:56320
	global_load_lds_dwordx4 v[214:215], off
	v_lshl_add_u64 v[214:215], v[244:245], 0, s[76:77]
	s_mov_b32 m0, s22
	s_nop 0
	global_load_lds_dwordx4 v[214:215], off
	s_barrier
; template <class Epi>
; __device__ __forceinline__ void gemm_phase(PG8_LAS unsigned char* lds, const Gemm g, const Sched& S, const Epi& E) {
;     ...
;             PG8_BAR; PG8_WAIT_L(0); PG8_MMA(1, 0, At, B0); PG8_BAR; PG8_SCHED;
;             PG8_STAGE(PG8_SB(1, 1), b3 + hsB, voffB);
;             PG8_WAIT_V(6); PG8_BAR; PG8_MMA(1, 1, At, B1); PG8_BAR;
;   __device__ __forceinline__ void operator()(const f32x4 (&acc)[2][2][4][2], const pg8::Unit& u, int wr, int wc, int fr, int fq) const {
;     ...
;       const float* md0 = modp + ((size_t)layer * 3 + condof(u.pm * 256)) * NMOD + slot * D;
; #pragma unroll
;       for (int bj = 0; bj < 2; ++bj)
; #pragma unroll
;         for (int n = 0; n < 2; ++n) {
;           float4 t = *(const float4*)(md0 + u.pn * 256 + bj * 128 + wc * 32 + n * 16 + fq * 4);
;           gsv[bj][n] = make_float4(t.x * scale, t.y * scale, t.z * scale, t.w * scale);
;         }
;     }
; #pragma unroll
;     for (int ai = 0; ai < 2; ++ai)
; #pragma unroll
;       for (int m = 0; m < 4; ++m) {
;         const int row = u.pm * 256 + ai * 128 + wr * 64 + m * 16 + fr;
;         if (kind == EPI_SWIGLU) {
; #pragma unroll
;           for (int bj = 0; bj < 2; ++bj) {
;             int hc = u.pn * 128 + bj * 64 + wc * 16 + fq * 4;
;             f32x4 g = acc[ai][bj][m][0], up = acc[ai][bj][m][1];
;             uint2 o; o.x = pack2(siluf_(g[0]) * up[0], siluf_(g[1]) * up[1]); o.y = pack2(siluf_(g[2]) * up[2], siluf_(g[3]) * up[3]);
;             *(uint2*)(outb + (size_t)row * ldo + hc) = o;
;           }
;         } else if (kind == EPI_RESID) {
;           float* xb;
;           { int b_ = row >= TPB ? 1 : 0; int u_ = row - b_ * TPB;
;             xb = (u_ < CTX) ? xctx + (size_t)(b_ * CTX + u_) * D : xout + ((size_t)b_ * SEQ + (u_ - CTX)) * D; }
;           const float* xr = (xb >= xout && xb < xout + (size_t)2 * SEQ * D) ? xin + (xb - xout) : xb;
; #pragma unroll
;           for (int bj = 0; bj < 2; ++bj)
; #pragma unroll
;             for (int n = 0; n < 2; ++n) {
;               int cc = u.pn * 256 + bj * 128 + wc * 32 + n * 16 + fq * 4;
;               const float4 gs = gsv[bj][n];
;               float4 xv = *(const float4*)(xr + cc);
;               f32x4 a = acc[ai][bj][m][n];
;               xv.x += gs.x * a[0]; xv.y += gs.y * a[1]; xv.z += gs.z * a[2]; xv.w += gs.w * a[3];
;               *(float4*)(xb + cc) = xv;
;             }
	s_waitcnt lgkmcnt(0)
	s_setprio 1
	s_waitcnt lgkmcnt(0)
	v_mfma_f32_16x16x32_bf16 v[60:63], v[80:83], v[152:155], v[60:63]
	v_mfma_f32_16x16x32_bf16 v[56:59], v[88:91], v[152:155], v[56:59]
	v_mfma_f32_16x16x32_bf16 v[44:47], v[80:83], v[178:181], v[44:47]
	v_mfma_f32_16x16x32_bf16 v[40:43], v[88:91], v[178:181], v[40:43]
	v_mfma_f32_16x16x32_bf16 v[28:31], v[80:83], v[186:189], v[28:31]
	v_mfma_f32_16x16x32_bf16 v[24:27], v[88:91], v[186:189], v[24:27]
	v_mfma_f32_16x16x32_bf16 v[12:15], v[80:83], v[194:197], v[12:15]
	v_mfma_f32_16x16x32_bf16 v[8:11], v[88:91], v[194:197], v[8:11]
	v_mfma_f32_16x16x32_bf16 v[60:63], v[84:87], v[172:175], v[60:63]
	v_mfma_f32_16x16x32_bf16 v[56:59], v[96:99], v[172:175], v[56:59]
	v_mfma_f32_16x16x32_bf16 v[44:47], v[84:87], v[182:185], v[44:47]
	v_mfma_f32_16x16x32_bf16 v[40:43], v[96:99], v[182:185], v[40:43]
	v_mfma_f32_16x16x32_bf16 v[28:31], v[84:87], v[190:193], v[28:31]
	v_mfma_f32_16x16x32_bf16 v[24:27], v[96:99], v[190:193], v[24:27]
	v_mfma_f32_16x16x32_bf16 v[12:15], v[84:87], v[198:201], v[12:15]
	v_mfma_f32_16x16x32_bf16 v[8:11], v[96:99], v[198:201], v[8:11]
	s_setprio 0
	s_barrier
	s_add_u32 s8, s8, 0x40080
	s_addc_u32 s9, s9, 0
	s_add_i32 s10, s10, s14
	v_lshl_add_u64 v[80:81], s[8:9], 0, v[144:145]
	s_mov_b32 m0, s10
	s_nop 0
	global_load_lds_dwordx4 v[80:81], off
	v_lshl_add_u64 v[80:81], s[8:9], 0, v[146:147]
	s_add_i32 m0, s10, 0x2000
	s_nop 0
	global_load_lds_dwordx4 v[80:81], off
	s_waitcnt vmcnt(6)
	s_barrier
	s_setprio 1
	v_mfma_f32_16x16x32_bf16 v[52:55], v[202:205], v[152:155], v[52:55]
	v_mfma_f32_16x16x32_bf16 v[48:51], v[210:213], v[152:155], v[48:51]
	v_mfma_f32_16x16x32_bf16 v[36:39], v[202:205], v[178:181], v[36:39]
	v_mfma_f32_16x16x32_bf16 v[32:35], v[210:213], v[178:181], v[32:35]
	v_mfma_f32_16x16x32_bf16 v[20:23], v[202:205], v[186:189], v[20:23]
	v_mfma_f32_16x16x32_bf16 v[16:19], v[210:213], v[186:189], v[16:19]
	v_mfma_f32_16x16x32_bf16 v[4:7], v[202:205], v[194:197], v[4:7]
	v_mfma_f32_16x16x32_bf16 v[0:3], v[210:213], v[194:197], v[0:3]
	v_mfma_f32_16x16x32_bf16 v[52:55], v[206:209], v[172:175], v[52:55]
	v_mfma_f32_16x16x32_bf16 v[48:51], v[236:239], v[172:175], v[48:51]
	v_mfma_f32_16x16x32_bf16 v[36:39], v[206:209], v[182:185], v[36:39]
	v_mfma_f32_16x16x32_bf16 v[32:35], v[236:239], v[182:185], v[32:35]
	v_mfma_f32_16x16x32_bf16 v[20:23], v[206:209], v[190:193], v[20:23]
	v_mfma_f32_16x16x32_bf16 v[16:19], v[236:239], v[190:193], v[16:19]
	v_mfma_f32_16x16x32_bf16 v[4:7], v[206:209], v[198:201], v[4:7]
	v_mfma_f32_16x16x32_bf16 v[0:3], v[236:239], v[198:201], v[0:3]
	s_setprio 0
	s_add_i32 s38, s38, 2
	s_add_u32 s6, s6, 0x100
	s_addc_u32 s7, s7, 0
	s_add_u32 s36, s36, 0x100
	s_addc_u32 s37, s37, 0
	s_cmp_gt_u32 s38, 13
	s_barrier
	s_cbranch_scc0 .LBB0_347
	s_lshl_b32 s8, s42, 8
	s_cmp_gt_i32 s42, 32
	s_cselect_b64 s[2:3], -1, 0
	v_cndmask_b32_e64 v80, 0, 1, s[2:3]
	s_and_b64 s[2:3], s[2:3], exec
	s_cselect_b32 s2, 0xffffdf00, 0
	s_add_i32 s2, s2, s8
	s_cmpk_gt_i32 s2, 0xff
	v_readfirstlane_b32 s2, v80
	s_cselect_b32 s2, s2, 2
	s_add_i32 s2, s2, s24
	s_mul_i32 s2, s2, 0x9000
	s_add_u32 s6, s25, s2
	s_addc_u32 s7, s26, 0
	s_lshl_b32 s4, s4, 8
	s_ashr_i32 s5, s4, 31
	s_lshl_b64 s[2:3], s[4:5], 2
	s_add_u32 s2, s6, s2
	s_addc_u32 s3, s7, s3
	s_add_u32 s2, s2, s29
	s_addc_u32 s3, s3, 0
	global_load_dwordx4 v[96:99], v163, s[2:3]
	global_load_dwordx4 v[88:91], v163, s[2:3] offset:64
	global_load_dwordx4 v[84:87], v163, s[2:3] offset:512
	global_load_dwordx4 v[80:83], v163, s[2:3] offset:576
	v_add_u32_e32 v171, s8, v156
	s_movk_i32 s2, 0x20ff
	v_cmp_lt_i32_e32 vcc, s2, v171
	s_nop 1
	v_cndmask_b32_e32 v152, 0, v228, vcc
	v_add_u32_e32 v166, v152, v171
	v_cmp_lt_i32_e64 s[42:43], s81, v166
	s_and_saveexec_b64 s[2:3], s[42:43]
	s_xor_b64 s[2:3], exec, s[2:3]
	v_cndmask_b32_e32 v152, 0, v230, vcc
	s_movk_i32 s5, 0xff00
	v_add3_u32 v166, v166, v152, s5
	v_mov_b64_e32 v[152:153], v[166:167]
	s_or_saveexec_b64 s[6:7], s[2:3]
	v_mov_b64_e32 v[154:155], s[44:45]
	s_xor_b64 exec, exec, s[6:7]
	v_cndmask_b32_e32 v152, 0, v229, vcc
	v_add_u32_e32 v152, v166, v152
	v_ashrrev_i32_e32 v153, 31, v152
	v_mov_b64_e32 v[154:155], s[48:49]
	s_or_b64 exec, exec, s[6:7]
	v_lshlrev_b64 v[152:153], 12, v[152:153]
	v_lshl_add_u64 v[154:155], v[154:155], 0, v[152:153]
	v_cmp_le_u64_e32 vcc, s[44:45], v[154:155]
	v_cmp_gt_u64_e64 s[42:43], s[56:57], v[154:155]
	s_and_b64 vcc, vcc, s[42:43]
	v_subrev_co_u32_e64 v152, s[42:43], s44, v154
	v_mov_b32_e32 v153, s45
	s_nop 0
	v_subb_co_u32_e64 v153, s[42:43], v155, v153, s[42:43]
	v_lshl_add_u64 v[152:153], s[44:45], 0, v[152:153]
	v_cndmask_b32_e32 v172, v154, v152, vcc
	v_or_b32_e32 v152, s4, v158
	v_cndmask_b32_e32 v173, v155, v153, vcc
	v_ashrrev_i32_e32 v153, 31, v152
	v_lshlrev_b64 v[152:153], 2, v[152:153]
	v_lshl_add_u64 v[178:179], v[172:173], 0, v[152:153]
	global_load_dwordx4 v[172:175], v[178:179], off
	global_load_dwordx4 v[180:183], v[178:179], off offset:64
	global_load_dwordx4 v[184:187], v[178:179], off offset:512
	global_load_dwordx4 v[188:191], v[178:179], off offset:576
	v_lshl_add_u64 v[154:155], v[154:155], 0, v[152:153]
	s_movk_i32 s2, 0x20ff
	s_waitcnt vmcnt(3)
	v_pk_fma_f32 v[140:141], v[140:141], v[96:97], v[172:173]
	v_pk_fma_f32 v[142:143], v[142:143], v[98:99], v[174:175]
	global_store_dwordx4 v[154:155], v[140:143], off
	s_waitcnt vmcnt(3)
	v_pk_fma_f32 v[136:137], v[136:137], v[88:89], v[180:181]
	v_pk_fma_f32 v[138:139], v[138:139], v[90:91], v[182:183]
	global_store_dwordx4 v[154:155], v[136:139], off offset:64
	s_waitcnt vmcnt(3)
;   __device__ __forceinline__ void operator()(const f32x4 (&acc)[2][2][4][2], const pg8::Unit& u, int wr, int wc, int fr, int fq) const {
;     ...
;           float* xb;
;           { int b_ = row >= TPB ? 1 : 0; int u_ = row - b_ * TPB;
;             xb = (u_ < CTX) ? xctx + (size_t)(b_ * CTX + u_) * D : xout + ((size_t)b_ * SEQ + (u_ - CTX)) * D; }
;           const float* xr = (xb >= xout && xb < xout + (size_t)2 * SEQ * D) ? xin + (xb - xout) : xb;
; #pragma unroll
;           for (int bj = 0; bj < 2; ++bj)
; #pragma unroll
;             for (int n = 0; n < 2; ++n) {
;               int cc = u.pn * 256 + bj * 128 + wc * 32 + n * 16 + fq * 4;
;               const float4 gs = gsv[bj][n];
;               float4 xv = *(const float4*)(xr + cc);
;               f32x4 a = acc[ai][bj][m][n];
;               xv.x += gs.x * a[0]; xv.y += gs.y * a[1]; xv.z += gs.z * a[2]; xv.w += gs.w * a[3];
;               *(float4*)(xb + cc) = xv;
;             }
	v_pk_fma_f32 v[132:133], v[132:133], v[84:85], v[184:185]
	v_pk_fma_f32 v[134:135], v[134:135], v[86:87], v[186:187]
	global_store_dwordx4 v[154:155], v[132:135], off offset:512
	s_waitcnt vmcnt(3)
	v_pk_fma_f32 v[128:129], v[128:129], v[80:81], v[188:189]
	v_pk_fma_f32 v[130:131], v[130:131], v[82:83], v[190:191]
	global_store_dwordx4 v[154:155], v[128:131], off offset:576
	s_nop 1
	v_add_u32_e32 v128, s8, v159
	v_cmp_lt_i32_e32 vcc, s2, v128
	s_nop 1
	v_cndmask_b32_e32 v129, 0, v228, vcc
	v_add_u32_e32 v132, v129, v128
	v_cmp_lt_i32_e64 s[42:43], s81, v132
	s_and_saveexec_b64 s[2:3], s[42:43]
	s_xor_b64 s[2:3], exec, s[2:3]
	v_cndmask_b32_e32 v128, 0, v230, vcc
	s_movk_i32 s4, 0xff00
	v_add3_u32 v166, v132, v128, s4
	v_mov_b64_e32 v[128:129], v[166:167]
	s_or_saveexec_b64 s[4:5], s[2:3]
	v_mov_b64_e32 v[130:131], s[44:45]
	s_xor_b64 exec, exec, s[4:5]
	v_cndmask_b32_e32 v128, 0, v229, vcc
	v_add_u32_e32 v128, v132, v128
	v_ashrrev_i32_e32 v129, 31, v128
	v_mov_b64_e32 v[130:131], s[48:49]
	s_or_b64 exec, exec, s[4:5]
	v_lshlrev_b64 v[128:129], 12, v[128:129]
	v_lshl_add_u64 v[128:129], v[130:131], 0, v[128:129]
	v_cmp_le_u64_e32 vcc, s[44:45], v[128:129]
	v_cmp_gt_u64_e64 s[42:43], s[56:57], v[128:129]
	s_and_b64 vcc, vcc, s[42:43]
	v_subrev_co_u32_e64 v130, s[42:43], s44, v128
	v_mov_b32_e32 v131, s45
	s_nop 0
	v_subb_co_u32_e64 v131, s[42:43], v129, v131, s[42:43]
	v_lshl_add_u64 v[130:131], s[44:45], 0, v[130:131]
	v_cndmask_b32_e32 v131, v129, v131, vcc
	v_cndmask_b32_e32 v130, v128, v130, vcc
	v_lshl_add_u64 v[132:133], v[130:131], 0, v[152:153]
	v_lshl_add_u64 v[134:135], v[128:129], 0, v[152:153]
	global_load_dwordx4 v[128:131], v[132:133], off
	global_load_dwordx4 v[180:183], v[132:133], off offset:64
	global_load_dwordx4 v[184:187], v[132:133], off offset:512
	global_load_dwordx4 v[188:191], v[132:133], off offset:576
	s_movk_i32 s2, 0x20ff
	s_waitcnt vmcnt(3)
	v_pk_fma_f32 v[124:125], v[124:125], v[96:97], v[128:129]
	v_pk_fma_f32 v[126:127], v[126:127], v[98:99], v[130:131]
	global_store_dwordx4 v[134:135], v[124:127], off
	s_waitcnt vmcnt(3)
	v_pk_fma_f32 v[120:121], v[120:121], v[88:89], v[180:181]
	v_pk_fma_f32 v[122:123], v[122:123], v[90:91], v[182:183]
	global_store_dwordx4 v[134:135], v[120:123], off offset:64
	s_waitcnt vmcnt(3)
	v_pk_fma_f32 v[116:117], v[116:117], v[84:85], v[184:185]
	v_pk_fma_f32 v[118:119], v[118:119], v[86:87], v[186:187]
	global_store_dwordx4 v[134:135], v[116:119], off offset:512
	s_waitcnt vmcnt(3)
	v_pk_fma_f32 v[112:113], v[112:113], v[80:81], v[188:189]
	v_pk_fma_f32 v[114:115], v[114:115], v[82:83], v[190:191]
	global_store_dwordx4 v[134:135], v[112:115], off offset:576
	s_nop 1
	v_add_u32_e32 v112, s8, v160
	v_cmp_lt_i32_e32 vcc, s2, v112
	s_nop 1
	v_cndmask_b32_e32 v113, 0, v228, vcc
	v_add_u32_e32 v116, v113, v112
	v_cmp_lt_i32_e64 s[42:43], s81, v116
	s_and_saveexec_b64 s[2:3], s[42:43]
	s_xor_b64 s[2:3], exec, s[2:3]
	v_cndmask_b32_e32 v112, 0, v230, vcc
	s_movk_i32 s4, 0xff00
	v_add3_u32 v166, v116, v112, s4
	v_mov_b64_e32 v[112:113], v[166:167]
	s_or_saveexec_b64 s[4:5], s[2:3]
	v_mov_b64_e32 v[114:115], s[44:45]
	s_xor_b64 exec, exec, s[4:5]
	v_cndmask_b32_e32 v112, 0, v229, vcc
	v_add_u32_e32 v112, v116, v112
	v_ashrrev_i32_e32 v113, 31, v112
	v_mov_b64_e32 v[114:115], s[48:49]
	s_or_b64 exec, exec, s[4:5]
	v_lshlrev_b64 v[112:113], 12, v[112:113]
	v_lshl_add_u64 v[112:113], v[114:115], 0, v[112:113]
	v_cmp_le_u64_e32 vcc, s[44:45], v[112:113]
	v_cmp_gt_u64_e64 s[42:43], s[56:57], v[112:113]
	s_and_b64 vcc, vcc, s[42:43]
	v_subrev_co_u32_e64 v114, s[42:43], s44, v112
	v_mov_b32_e32 v115, s45
	s_nop 0
	v_subb_co_u32_e64 v115, s[42:43], v113, v115, s[42:43]
	v_lshl_add_u64 v[114:115], s[44:45], 0, v[114:115]
	v_cndmask_b32_e32 v115, v113, v115, vcc
	v_cndmask_b32_e32 v114, v112, v114, vcc
	v_lshl_add_u64 v[116:117], v[114:115], 0, v[152:153]
	v_lshl_add_u64 v[118:119], v[112:113], 0, v[152:153]
	global_load_dwordx4 v[112:115], v[116:117], off
	global_load_dwordx4 v[180:183], v[116:117], off offset:64
	global_load_dwordx4 v[184:187], v[116:117], off offset:512
	global_load_dwordx4 v[188:191], v[116:117], off offset:576
	s_movk_i32 s2, 0x20ff
	s_waitcnt vmcnt(3)
	v_pk_fma_f32 v[108:109], v[108:109], v[96:97], v[112:113]
	v_pk_fma_f32 v[110:111], v[110:111], v[98:99], v[114:115]
	global_store_dwordx4 v[118:119], v[108:111], off
	s_waitcnt vmcnt(3)
	v_pk_fma_f32 v[104:105], v[104:105], v[88:89], v[180:181]
	v_pk_fma_f32 v[106:107], v[106:107], v[90:91], v[182:183]
	global_store_dwordx4 v[118:119], v[104:107], off offset:64
	s_waitcnt vmcnt(3)
	v_pk_fma_f32 v[100:101], v[100:101], v[84:85], v[184:185]
	v_pk_fma_f32 v[102:103], v[102:103], v[86:87], v[186:187]
	global_store_dwordx4 v[118:119], v[100:103], off offset:512
	s_waitcnt vmcnt(3)
	v_pk_fma_f32 v[92:93], v[92:93], v[80:81], v[188:189]
	v_pk_fma_f32 v[94:95], v[94:95], v[82:83], v[190:191]
	global_store_dwordx4 v[118:119], v[92:95], off offset:576
	s_nop 1
	v_add_u32_e32 v92, s8, v161
	v_cmp_lt_i32_e32 vcc, s2, v92
	s_nop 1
	v_cndmask_b32_e32 v93, 0, v228, vcc
	v_add_u32_e32 v100, v93, v92
	v_cmp_lt_i32_e64 s[42:43], s81, v100
	s_and_saveexec_b64 s[2:3], s[42:43]
	s_xor_b64 s[2:3], exec, s[2:3]
	v_cndmask_b32_e32 v92, 0, v230, vcc
	s_movk_i32 s4, 0xff00
	v_add3_u32 v166, v100, v92, s4
	v_mov_b64_e32 v[92:93], v[166:167]
	s_or_saveexec_b64 s[4:5], s[2:3]
	v_mov_b64_e32 v[94:95], s[44:45]
	s_xor_b64 exec, exec, s[4:5]
	v_cndmask_b32_e32 v92, 0, v229, vcc
	v_add_u32_e32 v92, v100, v92
	v_ashrrev_i32_e32 v93, 31, v92
	v_mov_b64_e32 v[94:95], s[48:49]
	s_or_b64 exec, exec, s[4:5]
	v_lshlrev_b64 v[92:93], 12, v[92:93]
	v_lshl_add_u64 v[92:93], v[94:95], 0, v[92:93]
	v_cmp_le_u64_e32 vcc, s[44:45], v[92:93]
	v_cmp_gt_u64_e64 s[42:43], s[56:57], v[92:93]
	s_and_b64 vcc, vcc, s[42:43]
	v_subrev_co_u32_e64 v94, s[42:43], s44, v92
	v_mov_b32_e32 v95, s45
	s_nop 0
	v_subb_co_u32_e64 v95, s[42:43], v93, v95, s[42:43]
	v_lshl_add_u64 v[94:95], s[44:45], 0, v[94:95]
	v_cndmask_b32_e32 v95, v93, v95, vcc
	v_cndmask_b32_e32 v94, v92, v94, vcc
	v_lshl_add_u64 v[100:101], v[94:95], 0, v[152:153]
	v_lshl_add_u64 v[102:103], v[92:93], 0, v[152:153]
	global_load_dwordx4 v[92:95], v[100:101], off
	global_load_dwordx4 v[180:183], v[100:101], off offset:64
	global_load_dwordx4 v[184:187], v[100:101], off offset:512
	global_load_dwordx4 v[188:191], v[100:101], off offset:576
	s_movk_i32 s2, 0x20ff
	s_waitcnt vmcnt(3)
;   __device__ __forceinline__ void operator()(const f32x4 (&acc)[2][2][4][2], const pg8::Unit& u, int wr, int wc, int fr, int fq) const {
;     ...
;           float* xb;
;           { int b_ = row >= TPB ? 1 : 0; int u_ = row - b_ * TPB;
;             xb = (u_ < CTX) ? xctx + (size_t)(b_ * CTX + u_) * D : xout + ((size_t)b_ * SEQ + (u_ - CTX)) * D; }
;           const float* xr = (xb >= xout && xb < xout + (size_t)2 * SEQ * D) ? xin + (xb - xout) : xb;
; #pragma unroll
;           for (int bj = 0; bj < 2; ++bj)
; #pragma unroll
;             for (int n = 0; n < 2; ++n) {
;               int cc = u.pn * 256 + bj * 128 + wc * 32 + n * 16 + fq * 4;
;               const float4 gs = gsv[bj][n];
;               float4 xv = *(const float4*)(xr + cc);
;               f32x4 a = acc[ai][bj][m][n];
;               xv.x += gs.x * a[0]; xv.y += gs.y * a[1]; xv.z += gs.z * a[2]; xv.w += gs.w * a[3];
;               *(float4*)(xb + cc) = xv;
;             }
	v_pk_fma_f32 v[76:77], v[76:77], v[96:97], v[92:93]
	v_pk_fma_f32 v[78:79], v[78:79], v[98:99], v[94:95]
	global_store_dwordx4 v[102:103], v[76:79], off
	s_waitcnt vmcnt(3)
	v_pk_fma_f32 v[72:73], v[72:73], v[88:89], v[180:181]
	v_pk_fma_f32 v[74:75], v[74:75], v[90:91], v[182:183]
	global_store_dwordx4 v[102:103], v[72:75], off offset:64
	s_waitcnt vmcnt(3)
	v_pk_fma_f32 v[68:69], v[68:69], v[84:85], v[184:185]
	v_pk_fma_f32 v[70:71], v[70:71], v[86:87], v[186:187]
	global_store_dwordx4 v[102:103], v[68:71], off offset:512
	s_waitcnt vmcnt(3)
	v_pk_fma_f32 v[64:65], v[64:65], v[80:81], v[188:189]
	v_pk_fma_f32 v[66:67], v[66:67], v[82:83], v[190:191]
	global_store_dwordx4 v[102:103], v[64:67], off offset:576
	s_nop 1
	v_add_u32_e32 v64, 0x80, v171
	v_cmp_lt_i32_e32 vcc, s2, v64
	s_nop 1
	v_cndmask_b32_e32 v65, 0, v228, vcc
	v_add_u32_e32 v68, v65, v64
	v_cmp_lt_i32_e64 s[42:43], s81, v68
	s_and_saveexec_b64 s[2:3], s[42:43]
	s_xor_b64 s[2:3], exec, s[2:3]
	v_cndmask_b32_e32 v64, 0, v230, vcc
	s_movk_i32 s4, 0xff00
	v_add3_u32 v166, v68, v64, s4
	v_mov_b64_e32 v[64:65], v[166:167]
	s_or_saveexec_b64 s[4:5], s[2:3]
	v_mov_b64_e32 v[66:67], s[44:45]
	s_xor_b64 exec, exec, s[4:5]
	v_cndmask_b32_e32 v64, 0, v229, vcc
	v_add_u32_e32 v64, v68, v64
	v_ashrrev_i32_e32 v65, 31, v64
	v_mov_b64_e32 v[66:67], s[48:49]
	s_or_b64 exec, exec, s[4:5]
	v_lshlrev_b64 v[64:65], 12, v[64:65]
	v_lshl_add_u64 v[64:65], v[66:67], 0, v[64:65]
	v_cmp_le_u64_e32 vcc, s[44:45], v[64:65]
	v_cmp_gt_u64_e64 s[42:43], s[56:57], v[64:65]
	s_and_b64 vcc, vcc, s[42:43]
	v_subrev_co_u32_e64 v66, s[42:43], s44, v64
	v_mov_b32_e32 v67, s45
	s_nop 0
	v_subb_co_u32_e64 v67, s[42:43], v65, v67, s[42:43]
	v_lshl_add_u64 v[66:67], s[44:45], 0, v[66:67]
	v_cndmask_b32_e32 v67, v65, v67, vcc
	v_cndmask_b32_e32 v66, v64, v66, vcc
	v_lshl_add_u64 v[68:69], v[66:67], 0, v[152:153]
	v_lshl_add_u64 v[70:71], v[64:65], 0, v[152:153]
	global_load_dwordx4 v[64:67], v[68:69], off
	global_load_dwordx4 v[180:183], v[68:69], off offset:64
	global_load_dwordx4 v[184:187], v[68:69], off offset:512
	global_load_dwordx4 v[188:191], v[68:69], off offset:576
	s_movk_i32 s2, 0x20ff
	s_waitcnt vmcnt(3)
	v_pk_fma_f32 v[60:61], v[60:61], v[96:97], v[64:65]
	v_pk_fma_f32 v[62:63], v[62:63], v[98:99], v[66:67]
	global_store_dwordx4 v[70:71], v[60:63], off
	s_waitcnt vmcnt(3)
	v_pk_fma_f32 v[56:57], v[56:57], v[88:89], v[180:181]
	v_pk_fma_f32 v[58:59], v[58:59], v[90:91], v[182:183]
	global_store_dwordx4 v[70:71], v[56:59], off offset:64
	s_waitcnt vmcnt(3)
	v_pk_fma_f32 v[52:53], v[52:53], v[84:85], v[184:185]
	v_pk_fma_f32 v[54:55], v[54:55], v[86:87], v[186:187]
	global_store_dwordx4 v[70:71], v[52:55], off offset:512
	s_waitcnt vmcnt(3)
	v_pk_fma_f32 v[48:49], v[48:49], v[80:81], v[188:189]
	v_pk_fma_f32 v[50:51], v[50:51], v[82:83], v[190:191]
	global_store_dwordx4 v[70:71], v[48:51], off offset:576
	s_nop 1
	v_add_u32_e32 v48, 0x90, v171
	v_cmp_lt_i32_e32 vcc, s2, v48
	s_nop 1
	v_cndmask_b32_e32 v49, 0, v228, vcc
	v_add_u32_e32 v52, v49, v48
	v_cmp_lt_i32_e64 s[42:43], s81, v52
	s_and_saveexec_b64 s[2:3], s[42:43]
	s_xor_b64 s[2:3], exec, s[2:3]
	v_cndmask_b32_e32 v48, 0, v230, vcc
	s_movk_i32 s4, 0xff00
	v_add3_u32 v166, v52, v48, s4
	v_mov_b64_e32 v[48:49], v[166:167]
	s_or_saveexec_b64 s[4:5], s[2:3]
	v_mov_b64_e32 v[50:51], s[44:45]
	s_xor_b64 exec, exec, s[4:5]
	v_cndmask_b32_e32 v48, 0, v229, vcc
	v_add_u32_e32 v48, v52, v48
	v_ashrrev_i32_e32 v49, 31, v48
	v_mov_b64_e32 v[50:51], s[48:49]
	s_or_b64 exec, exec, s[4:5]
	v_lshlrev_b64 v[48:49], 12, v[48:49]
	v_lshl_add_u64 v[48:49], v[50:51], 0, v[48:49]
	v_cmp_le_u64_e32 vcc, s[44:45], v[48:49]
	v_cmp_gt_u64_e64 s[42:43], s[56:57], v[48:49]
	s_and_b64 vcc, vcc, s[42:43]
	v_subrev_co_u32_e64 v50, s[42:43], s44, v48
	v_mov_b32_e32 v51, s45
	s_nop 0
	v_subb_co_u32_e64 v51, s[42:43], v49, v51, s[42:43]
	v_lshl_add_u64 v[50:51], s[44:45], 0, v[50:51]
	v_cndmask_b32_e32 v51, v49, v51, vcc
	v_cndmask_b32_e32 v50, v48, v50, vcc
	v_lshl_add_u64 v[52:53], v[50:51], 0, v[152:153]
	v_lshl_add_u64 v[54:55], v[48:49], 0, v[152:153]
	global_load_dwordx4 v[48:51], v[52:53], off
	global_load_dwordx4 v[180:183], v[52:53], off offset:64
	global_load_dwordx4 v[184:187], v[52:53], off offset:512
	global_load_dwordx4 v[188:191], v[52:53], off offset:576
	s_movk_i32 s2, 0x20ff
	s_waitcnt vmcnt(3)
;   __device__ __forceinline__ void operator()(const f32x4 (&acc)[2][2][4][2], const pg8::Unit& u, int wr, int wc, int fr, int fq) const {
;     ...
;           float* xb;
;           { int b_ = row >= TPB ? 1 : 0; int u_ = row - b_ * TPB;
;             xb = (u_ < CTX) ? xctx + (size_t)(b_ * CTX + u_) * D : xout + ((size_t)b_ * SEQ + (u_ - CTX)) * D; }
;           const float* xr = (xb >= xout && xb < xout + (size_t)2 * SEQ * D) ? xin + (xb - xout) : xb;
; #pragma unroll
;           for (int bj = 0; bj < 2; ++bj)
; #pragma unroll
;             for (int n = 0; n < 2; ++n) {
;               int cc = u.pn * 256 + bj * 128 + wc * 32 + n * 16 + fq * 4;
;               const float4 gs = gsv[bj][n];
;               float4 xv = *(const float4*)(xr + cc);
;               f32x4 a = acc[ai][bj][m][n];
;               xv.x += gs.x * a[0]; xv.y += gs.y * a[1]; xv.z += gs.z * a[2]; xv.w += gs.w * a[3];
;               *(float4*)(xb + cc) = xv;
;             }
	v_pk_fma_f32 v[44:45], v[44:45], v[96:97], v[48:49]
	v_pk_fma_f32 v[46:47], v[46:47], v[98:99], v[50:51]
	global_store_dwordx4 v[54:55], v[44:47], off
	s_waitcnt vmcnt(3)
	v_pk_fma_f32 v[40:41], v[40:41], v[88:89], v[180:181]
	v_pk_fma_f32 v[42:43], v[42:43], v[90:91], v[182:183]
	global_store_dwordx4 v[54:55], v[40:43], off offset:64
	s_waitcnt vmcnt(3)
	v_pk_fma_f32 v[36:37], v[36:37], v[84:85], v[184:185]
	v_pk_fma_f32 v[38:39], v[38:39], v[86:87], v[186:187]
	global_store_dwordx4 v[54:55], v[36:39], off offset:512
	s_waitcnt vmcnt(3)
	v_pk_fma_f32 v[32:33], v[32:33], v[80:81], v[188:189]
	v_pk_fma_f32 v[34:35], v[34:35], v[82:83], v[190:191]
	global_store_dwordx4 v[54:55], v[32:35], off offset:576
	s_nop 1
	v_add_u32_e32 v32, 0xa0, v171
	v_cmp_lt_i32_e32 vcc, s2, v32
	s_nop 1
	v_cndmask_b32_e32 v33, 0, v228, vcc
	v_add_u32_e32 v36, v33, v32
	v_cmp_lt_i32_e64 s[42:43], s81, v36
	s_and_saveexec_b64 s[2:3], s[42:43]
	s_xor_b64 s[2:3], exec, s[2:3]
	v_cndmask_b32_e32 v32, 0, v230, vcc
	s_movk_i32 s4, 0xff00
	v_add3_u32 v166, v36, v32, s4
	v_mov_b64_e32 v[32:33], v[166:167]
	s_or_saveexec_b64 s[4:5], s[2:3]
	v_mov_b64_e32 v[34:35], s[44:45]
	s_xor_b64 exec, exec, s[4:5]
	v_cndmask_b32_e32 v32, 0, v229, vcc
	v_add_u32_e32 v32, v36, v32
	v_ashrrev_i32_e32 v33, 31, v32
	v_mov_b64_e32 v[34:35], s[48:49]
	s_or_b64 exec, exec, s[4:5]
	v_lshlrev_b64 v[32:33], 12, v[32:33]
	v_lshl_add_u64 v[32:33], v[34:35], 0, v[32:33]
	v_cmp_le_u64_e32 vcc, s[44:45], v[32:33]
	v_cmp_gt_u64_e64 s[42:43], s[56:57], v[32:33]
	s_and_b64 vcc, vcc, s[42:43]
	v_subrev_co_u32_e64 v34, s[42:43], s44, v32
	v_mov_b32_e32 v35, s45
	s_nop 0
	v_subb_co_u32_e64 v35, s[42:43], v33, v35, s[42:43]
	v_lshl_add_u64 v[34:35], s[44:45], 0, v[34:35]
	v_cndmask_b32_e32 v35, v33, v35, vcc
	v_cndmask_b32_e32 v34, v32, v34, vcc
	v_lshl_add_u64 v[36:37], v[34:35], 0, v[152:153]
	v_lshl_add_u64 v[38:39], v[32:33], 0, v[152:153]
	global_load_dwordx4 v[32:35], v[36:37], off
	global_load_dwordx4 v[180:183], v[36:37], off offset:64
	global_load_dwordx4 v[184:187], v[36:37], off offset:512
	global_load_dwordx4 v[188:191], v[36:37], off offset:576
	s_movk_i32 s2, 0x20ff
	s_waitcnt vmcnt(3)
	v_pk_fma_f32 v[28:29], v[28:29], v[96:97], v[32:33]
	v_pk_fma_f32 v[30:31], v[30:31], v[98:99], v[34:35]
	global_store_dwordx4 v[38:39], v[28:31], off
	s_waitcnt vmcnt(3)
	v_pk_fma_f32 v[24:25], v[24:25], v[88:89], v[180:181]
	v_pk_fma_f32 v[26:27], v[26:27], v[90:91], v[182:183]
	global_store_dwordx4 v[38:39], v[24:27], off offset:64
	s_waitcnt vmcnt(3)
	v_pk_fma_f32 v[20:21], v[20:21], v[84:85], v[184:185]
	v_pk_fma_f32 v[22:23], v[22:23], v[86:87], v[186:187]
	global_store_dwordx4 v[38:39], v[20:23], off offset:512
	s_waitcnt vmcnt(3)
	v_pk_fma_f32 v[16:17], v[16:17], v[80:81], v[188:189]
	v_pk_fma_f32 v[18:19], v[18:19], v[82:83], v[190:191]
	global_store_dwordx4 v[38:39], v[16:19], off offset:576
	s_nop 1
	v_add_u32_e32 v16, 0xb0, v171
	v_cmp_lt_i32_e32 vcc, s2, v16
	s_nop 1
	v_cndmask_b32_e32 v17, 0, v228, vcc
	v_add_u32_e32 v20, v17, v16
	v_cmp_lt_i32_e64 s[42:43], s81, v20
	s_and_saveexec_b64 s[2:3], s[42:43]
	s_xor_b64 s[2:3], exec, s[2:3]
	v_cndmask_b32_e32 v16, 0, v230, vcc
	s_movk_i32 s4, 0xff00
	v_add3_u32 v166, v20, v16, s4
	v_mov_b64_e32 v[16:17], v[166:167]
	s_or_saveexec_b64 s[4:5], s[2:3]
	v_mov_b64_e32 v[18:19], s[44:45]
	s_xor_b64 exec, exec, s[4:5]
	s_cbranch_execz .LBB0_339
	v_cndmask_b32_e32 v16, 0, v229, vcc
	v_add_u32_e32 v16, v20, v16
	v_ashrrev_i32_e32 v17, 31, v16
	v_mov_b64_e32 v[18:19], s[48:49]
	s_branch .LBB0_339

;   __device__ __forceinline__ void operator()(const f32x4 (&acc)[2][2][4][2], const pg8::Unit& u, int wr, int wc, int fr, int fq) const {
;     ...
;           float* xb;
;           { int b_ = row >= TPB ? 1 : 0; int u_ = row - b_ * TPB;
;             xb = (u_ < CTX) ? xctx + (size_t)(b_ * CTX + u_) * D : xout + ((size_t)b_ * SEQ + (u_ - CTX)) * D; }
;           const float* xr = (xb >= xout && xb < xout + (size_t)2 * SEQ * D) ? xin + (xb - xout) : xb;
; #pragma unroll
;           for (int bj = 0; bj < 2; ++bj)
; #pragma unroll
;             for (int n = 0; n < 2; ++n) {
;               int cc = u.pn * 256 + bj * 128 + wc * 32 + n * 16 + fq * 4;
;               const float4 gs = gsv[bj][n];
;               float4 xv = *(const float4*)(xr + cc);
;               f32x4 a = acc[ai][bj][m][n];
;               xv.x += gs.x * a[0]; xv.y += gs.y * a[1]; xv.z += gs.z * a[2]; xv.w += gs.w * a[3];
;               *(float4*)(xb + cc) = xv;
;             }
.LBB0_833:
	s_or_b64 exec, exec, s[4:5]
	v_lshlrev_b64 v[16:17], 12, v[16:17]
	v_lshl_add_u64 v[16:17], v[18:19], 0, v[16:17]
	v_cmp_le_u64_e32 vcc, s[48:49], v[16:17]
	v_cmp_gt_u64_e64 s[42:43], s[58:59], v[16:17]
	s_and_b64 vcc, vcc, s[42:43]
	v_subrev_co_u32_e64 v18, s[42:43], s48, v16
	v_mov_b32_e32 v19, s49
	s_nop 0
	v_subb_co_u32_e64 v19, s[42:43], v17, v19, s[42:43]
	v_lshl_add_u64 v[18:19], s[56:57], 0, v[18:19]
	v_cndmask_b32_e32 v19, v17, v19, vcc
	v_cndmask_b32_e32 v18, v16, v18, vcc
	v_lshl_add_u64 v[20:21], v[18:19], 0, v[134:135]
	v_lshl_add_u64 v[22:23], v[16:17], 0, v[134:135]
	global_load_dwordx4 v[16:19], v[20:21], off
	global_load_dwordx4 v[180:183], v[20:21], off offset:64
	global_load_dwordx4 v[184:187], v[20:21], off offset:512
	global_load_dwordx4 v[188:191], v[20:21], off offset:576
	s_and_b64 vcc, exec, s[40:41]
	s_mov_b32 s38, s36
	s_mov_b32 s39, s37
	s_mov_b64 s[6:7], s[44:45]
	s_mov_b64 s[4:5], s[60:61]
	s_waitcnt vmcnt(3)
	v_pk_fma_f32 v[12:13], v[12:13], v[152:153], v[16:17]
	v_pk_fma_f32 v[14:15], v[14:15], v[142:143], v[18:19]
	global_store_dwordx4 v[22:23], v[12:15], off
	s_waitcnt vmcnt(3)
	v_pk_fma_f32 v[8:9], v[8:9], v[140:141], v[180:181]
	v_pk_fma_f32 v[10:11], v[10:11], v[138:139], v[182:183]
	global_store_dwordx4 v[22:23], v[8:11], off offset:64
	s_waitcnt vmcnt(3)
	v_pk_fma_f32 v[4:5], v[4:5], v[136:137], v[184:185]
	v_pk_fma_f32 v[6:7], v[6:7], v[132:133], v[186:187]
	global_store_dwordx4 v[22:23], v[4:7], off offset:512
	s_waitcnt vmcnt(3)
	v_pk_fma_f32 v[0:1], v[0:1], v[128:129], v[188:189]
	v_pk_fma_f32 v[2:3], v[2:3], v[130:131], v[190:191]
	global_store_dwordx4 v[22:23], v[0:3], off offset:576
	s_cbranch_vccnz .LBB0_878

; #define PG8_STAGE(bufoff, gbase, voff) do { _Pragma("unroll") for (int _i = 0; _i < 2; ++_i) \
;         __builtin_amdgcn_global_load_lds((const unsigned*)((const char*)(gbase) + (voff)[_i]), (PG8_LAS unsigned*)(lds + (bufoff) + ldsw + _i * 8192), 16, 0, 0); } while (0)
; #define PG8_LDA(dst, b, h) do { _Pragma("unroll") for (int m = 0; m < 4; ++m) _Pragma("unroll") for (int k = 0; k < 2; ++k) dst[m][k] = *(const PG8_LAS bf16x8*)(lds + PG8_SA(b, h) + aoff + m * 2048 + k * 1024); } while (0)
; #define PG8_LDB(dst, b, h) do { _Pragma("unroll") for (int n = 0; n < 2; ++n) _Pragma("unroll") for (int k = 0; k < 2; ++k) dst[n][k] = *(const PG8_LAS bf16x8*)(lds + PG8_SB(b, h) + boff + n * 2048 + k * 1024); } while (0)
; #define PG8_MMA(ai, bj, At, Bt) do { __builtin_amdgcn_s_setprio(1); _Pragma("unroll") for (int m = 0; m < 4; ++m) _Pragma("unroll") for (int n = 0; n < 2; ++n) _Pragma("unroll") for (int k = 0; k < 2; ++k) \
;         acc[ai][bj][m][n] = __builtin_amdgcn_mfma_f32_16x16x32_bf16(Bt[n][k], At[m][k], acc[ai][bj][m][n], 0, 0, 0); __builtin_amdgcn_s_setprio(0); } while (0)
; #define PG8_WAIT_V(n) asm volatile("s_waitcnt vmcnt(" #n ")" ::: "memory")
; #define PG8_WAIT_L(n) asm volatile("s_waitcnt lgkmcnt(" #n ")" ::: "memory")
; #define PG8_BAR __builtin_amdgcn_s_barrier()
; #define PG8_SCHED __builtin_amdgcn_sched_barrier(0)
; template <class Epi>
; __device__ __forceinline__ void gemm_phase(PG8_LAS unsigned char* lds, const Gemm g, const Sched& S, const Epi& E) {
;     ...
;             PG8_LDB(B0, 0, 0); PG8_SCHED; PG8_LDA(At, 0, 0); PG8_STAGE(PG8_SA(1, 1), a1 + hsA, voffA);
;             PG8_WAIT_L(8); PG8_BAR; PG8_WAIT_L(0); PG8_MMA(0, 0, At, B0); PG8_BAR; PG8_SCHED;
;             PG8_LDB(B1, 0, 1); PG8_STAGE(PG8_SB(0, 0), b2, voffB);
;             PG8_BAR; PG8_WAIT_L(0); PG8_MMA(0, 1, At, B1); PG8_BAR;
;             PG8_LDA(At, 0, 1); PG8_STAGE(PG8_SA(0, 0), a2, voffA);
;             PG8_BAR; PG8_WAIT_L(0); PG8_MMA(1, 0, At, B0); PG8_BAR; PG8_SCHED;
;             PG8_STAGE(PG8_SB(0, 1), b2 + hsB, voffB);
;             PG8_WAIT_V(6); PG8_BAR; PG8_MMA(1, 1, At, B1); PG8_BAR;
.LBB0_845:
	s_add_u32 s6, s4, 0x100
	s_addc_u32 s7, s5, 0
	s_add_i32 s43, 0, 0x10000
	v_add_u32_e32 v140, s43, v159
	ds_read_b128 v[128:131], v140
	ds_read_b128 v[132:135], v140 offset:1024
	ds_read_b128 v[136:139], v140 offset:2048
	ds_read_b128 v[140:143], v140 offset:3072
	s_cmp_eq_u32 s42, 40
	s_cselect_b32 s11, s61, s7
	s_cselect_b32 s10, s60, s6
	s_cselect_b32 s9, s45, s3
	s_cselect_b32 s8, s44, s2
	v_lshl_add_u64 v[156:157], s[4:5], 0, v[148:149]
	s_add_i32 m0, s19, 0xc000
	ds_read_b128 v[152:155], v171
	ds_read_b128 v[180:183], v171 offset:1024
	ds_read_b128 v[184:187], v171 offset:2048
	ds_read_b128 v[188:191], v171 offset:3072
	ds_read_b128 v[192:195], v171 offset:4096
	ds_read_b128 v[196:199], v171 offset:5120
	ds_read_b128 v[200:203], v171 offset:6144
	ds_read_b128 v[204:207], v171 offset:7168
	global_load_lds_dwordx4 v[156:157], off
	v_lshl_add_u64 v[156:157], s[4:5], 0, v[150:151]
	s_add_i32 m0, s19, 0xe000
	s_nop 0
	global_load_lds_dwordx4 v[156:157], off
	s_waitcnt lgkmcnt(8)
	s_barrier
	s_waitcnt lgkmcnt(0)
	s_setprio 1
	s_waitcnt lgkmcnt(0)
	v_mfma_f32_16x16x32_bf16 v[124:127], v[128:131], v[152:155], v[124:127]
	v_mfma_f32_16x16x32_bf16 v[120:123], v[136:139], v[152:155], v[120:123]
	v_mfma_f32_16x16x32_bf16 v[108:111], v[128:131], v[184:187], v[108:111]
	v_mfma_f32_16x16x32_bf16 v[104:107], v[136:139], v[184:187], v[104:107]
	v_mfma_f32_16x16x32_bf16 v[92:95], v[128:131], v[192:195], v[92:95]
	v_mfma_f32_16x16x32_bf16 v[88:91], v[136:139], v[192:195], v[88:91]
	v_mfma_f32_16x16x32_bf16 v[76:79], v[128:131], v[200:203], v[76:79]
	v_mfma_f32_16x16x32_bf16 v[72:75], v[136:139], v[200:203], v[72:75]
	v_mfma_f32_16x16x32_bf16 v[124:127], v[132:135], v[180:183], v[124:127]
	v_mfma_f32_16x16x32_bf16 v[120:123], v[140:143], v[180:183], v[120:123]
	v_mfma_f32_16x16x32_bf16 v[108:111], v[132:135], v[188:191], v[108:111]
	v_mfma_f32_16x16x32_bf16 v[104:107], v[140:143], v[188:191], v[104:107]
	v_mfma_f32_16x16x32_bf16 v[92:95], v[132:135], v[196:199], v[92:95]
	v_mfma_f32_16x16x32_bf16 v[88:91], v[140:143], v[196:199], v[88:91]
	v_mfma_f32_16x16x32_bf16 v[76:79], v[132:135], v[204:207], v[76:79]
	v_mfma_f32_16x16x32_bf16 v[72:75], v[140:143], v[204:207], v[72:75]
	s_setprio 0
	s_barrier
	s_add_i32 s62, 0, 0x14000
	v_add_u32_e32 v156, s62, v159
	s_add_i32 s4, s43, s18
	ds_read_b128 v[208:211], v156
	ds_read_b128 v[212:215], v156 offset:1024
	ds_read_b128 v[236:239], v156 offset:2048
	ds_read_b128 v[240:243], v156 offset:3072
	v_lshl_add_u64 v[156:157], s[8:9], 0, v[144:145]
	s_mov_b32 m0, s4
	v_lshl_add_u64 v[172:173], s[8:9], 0, v[146:147]
	global_load_lds_dwordx4 v[156:157], off
	s_add_i32 m0, s4, 0x2000
	s_nop 0
	global_load_lds_dwordx4 v[172:173], off
	s_barrier
	s_waitcnt lgkmcnt(0)
	s_setprio 1
	s_waitcnt lgkmcnt(0)
	v_mfma_f32_16x16x32_bf16 v[116:119], v[208:211], v[152:155], v[116:119]
	v_mfma_f32_16x16x32_bf16 v[112:115], v[236:239], v[152:155], v[112:115]
	v_mfma_f32_16x16x32_bf16 v[100:103], v[208:211], v[184:187], v[100:103]
	v_mfma_f32_16x16x32_bf16 v[96:99], v[236:239], v[184:187], v[96:99]
	v_mfma_f32_16x16x32_bf16 v[84:87], v[208:211], v[192:195], v[84:87]
	v_mfma_f32_16x16x32_bf16 v[80:83], v[236:239], v[192:195], v[80:83]
	v_mfma_f32_16x16x32_bf16 v[68:71], v[208:211], v[200:203], v[68:71]
	v_mfma_f32_16x16x32_bf16 v[64:67], v[236:239], v[200:203], v[64:67]
	v_mfma_f32_16x16x32_bf16 v[116:119], v[212:215], v[180:183], v[116:119]
	v_mfma_f32_16x16x32_bf16 v[112:115], v[240:243], v[180:183], v[112:115]
	v_mfma_f32_16x16x32_bf16 v[100:103], v[212:215], v[188:191], v[100:103]
	v_mfma_f32_16x16x32_bf16 v[96:99], v[240:243], v[188:191], v[96:99]
	v_mfma_f32_16x16x32_bf16 v[84:87], v[212:215], v[196:199], v[84:87]
	v_mfma_f32_16x16x32_bf16 v[80:83], v[240:243], v[196:199], v[80:83]
	v_mfma_f32_16x16x32_bf16 v[68:71], v[212:215], v[204:207], v[68:71]
	v_mfma_f32_16x16x32_bf16 v[64:67], v[240:243], v[204:207], v[64:67]
	s_setprio 0
	s_mov_b32 m0, s19
	v_lshl_add_u64 v[174:175], s[10:11], 0, v[144:145]
	s_barrier
	ds_read_b128 v[152:155], v171 offset:16384
	ds_read_b128 v[180:183], v171 offset:17408
	ds_read_b128 v[184:187], v171 offset:18432
	ds_read_b128 v[188:191], v171 offset:19456
	ds_read_b128 v[192:195], v171 offset:20480
	ds_read_b128 v[196:199], v171 offset:21504
	ds_read_b128 v[200:203], v171 offset:22528
	ds_read_b128 v[204:207], v171 offset:23552
	global_load_lds_dwordx4 v[174:175], off
	v_lshl_add_u64 v[244:245], s[10:11], 0, v[146:147]
	s_mov_b32 m0, s20
	s_nop 0
	global_load_lds_dwordx4 v[244:245], off
	s_barrier
	s_waitcnt lgkmcnt(0)
	s_setprio 1
	s_waitcnt lgkmcnt(0)
	v_mfma_f32_16x16x32_bf16 v[60:63], v[128:131], v[152:155], v[60:63]
	v_mfma_f32_16x16x32_bf16 v[56:59], v[136:139], v[152:155], v[56:59]
	v_mfma_f32_16x16x32_bf16 v[44:47], v[128:131], v[184:187], v[44:47]
	v_mfma_f32_16x16x32_bf16 v[40:43], v[136:139], v[184:187], v[40:43]
	v_mfma_f32_16x16x32_bf16 v[28:31], v[128:131], v[192:195], v[28:31]
	v_mfma_f32_16x16x32_bf16 v[24:27], v[136:139], v[192:195], v[24:27]
	v_mfma_f32_16x16x32_bf16 v[12:15], v[128:131], v[200:203], v[12:15]
	v_mfma_f32_16x16x32_bf16 v[8:11], v[136:139], v[200:203], v[8:11]
	v_mfma_f32_16x16x32_bf16 v[60:63], v[132:135], v[180:183], v[60:63]
	v_mfma_f32_16x16x32_bf16 v[56:59], v[140:143], v[180:183], v[56:59]
	v_mfma_f32_16x16x32_bf16 v[44:47], v[132:135], v[188:191], v[44:47]
	v_mfma_f32_16x16x32_bf16 v[40:43], v[140:143], v[188:191], v[40:43]
	v_mfma_f32_16x16x32_bf16 v[28:31], v[132:135], v[196:199], v[28:31]
	v_mfma_f32_16x16x32_bf16 v[24:27], v[140:143], v[196:199], v[24:27]
	v_mfma_f32_16x16x32_bf16 v[12:15], v[132:135], v[204:207], v[12:15]
	v_mfma_f32_16x16x32_bf16 v[8:11], v[140:143], v[204:207], v[8:11]
	s_setprio 0
	s_barrier
; #define PG8_STAGE(bufoff, gbase, voff) do { _Pragma("unroll") for (int _i = 0; _i < 2; ++_i) \
;         __builtin_amdgcn_global_load_lds((const unsigned*)((const char*)(gbase) + (voff)[_i]), (PG8_LAS unsigned*)(lds + (bufoff) + ldsw + _i * 8192), 16, 0, 0); } while (0)
; #define PG8_LDA(dst, b, h) do { _Pragma("unroll") for (int m = 0; m < 4; ++m) _Pragma("unroll") for (int k = 0; k < 2; ++k) dst[m][k] = *(const PG8_LAS bf16x8*)(lds + PG8_SA(b, h) + aoff + m * 2048 + k * 1024); } while (0)
; #define PG8_LDB(dst, b, h) do { _Pragma("unroll") for (int n = 0; n < 2; ++n) _Pragma("unroll") for (int k = 0; k < 2; ++k) dst[n][k] = *(const PG8_LAS bf16x8*)(lds + PG8_SB(b, h) + boff + n * 2048 + k * 1024); } while (0)
; #define PG8_MMA(ai, bj, At, Bt) do { __builtin_amdgcn_s_setprio(1); _Pragma("unroll") for (int m = 0; m < 4; ++m) _Pragma("unroll") for (int n = 0; n < 2; ++n) _Pragma("unroll") for (int k = 0; k < 2; ++k) \
;         acc[ai][bj][m][n] = __builtin_amdgcn_mfma_f32_16x16x32_bf16(Bt[n][k], At[m][k], acc[ai][bj][m][n], 0, 0, 0); __builtin_amdgcn_s_setprio(0); } while (0)
; #define PG8_WAIT_V(n) asm volatile("s_waitcnt vmcnt(" #n ")" ::: "memory")
; #define PG8_WAIT_L(n) asm volatile("s_waitcnt lgkmcnt(" #n ")" ::: "memory")
; #define PG8_BAR __builtin_amdgcn_s_barrier()
; #define PG8_SCHED __builtin_amdgcn_sched_barrier(0)
; template <class Epi>
; __device__ __forceinline__ void gemm_phase(PG8_LAS unsigned char* lds, const Gemm g, const Sched& S, const Epi& E) {
;     ...
;             PG8_BAR; PG8_WAIT_L(0); PG8_MMA(1, 0, At, B0); PG8_BAR; PG8_SCHED;
;             PG8_STAGE(PG8_SB(0, 1), b2 + hsB, voffB);
;             PG8_WAIT_V(6); PG8_BAR; PG8_MMA(1, 1, At, B1); PG8_BAR;
;             PG8_LDB(B0, 1, 0); PG8_SCHED; PG8_LDA(At, 1, 0); PG8_STAGE(PG8_SA(0, 1), a2 + hsA, voffA);
;             PG8_WAIT_L(8); PG8_BAR; PG8_WAIT_L(0); PG8_MMA(0, 0, At, B0); PG8_BAR; PG8_SCHED;
;             PG8_LDB(B1, 1, 1); PG8_STAGE(PG8_SB(1, 0), b3, voffB);
;             PG8_BAR; PG8_WAIT_L(0); PG8_MMA(0, 1, At, B1); PG8_BAR;
;             PG8_LDA(At, 1, 1); PG8_STAGE(PG8_SA(1, 0), a3, voffA);
;             PG8_BAR; PG8_WAIT_L(0); PG8_MMA(1, 0, At, B0); PG8_BAR; PG8_SCHED;
;             PG8_STAGE(PG8_SB(1, 1), b3 + hsB, voffB);
;             PG8_WAIT_V(6); PG8_BAR; PG8_MMA(1, 1, At, B1); PG8_BAR;
	s_add_u32 s4, s8, 0xb0000
	s_addc_u32 s5, s9, 0
	s_add_i32 s43, s62, s18
	v_lshl_add_u64 v[128:129], s[4:5], 0, v[144:145]
	s_mov_b32 m0, s43
	s_nop 0
	global_load_lds_dwordx4 v[128:129], off
	v_lshl_add_u64 v[128:129], s[4:5], 0, v[146:147]
	s_add_i32 m0, s43, 0x2000
	s_nop 0
	global_load_lds_dwordx4 v[128:129], off
	s_waitcnt vmcnt(6)
	s_barrier
	s_setprio 1
	v_mfma_f32_16x16x32_bf16 v[52:55], v[208:211], v[152:155], v[52:55]
	v_mfma_f32_16x16x32_bf16 v[48:51], v[236:239], v[152:155], v[48:51]
	v_mfma_f32_16x16x32_bf16 v[36:39], v[208:211], v[184:187], v[36:39]
	v_mfma_f32_16x16x32_bf16 v[32:35], v[236:239], v[184:187], v[32:35]
	v_mfma_f32_16x16x32_bf16 v[20:23], v[208:211], v[192:195], v[20:23]
	v_mfma_f32_16x16x32_bf16 v[16:19], v[236:239], v[192:195], v[16:19]
	v_mfma_f32_16x16x32_bf16 v[4:7], v[208:211], v[200:203], v[4:7]
	v_mfma_f32_16x16x32_bf16 v[0:3], v[236:239], v[200:203], v[0:3]
	v_mfma_f32_16x16x32_bf16 v[52:55], v[212:215], v[180:183], v[52:55]
	v_mfma_f32_16x16x32_bf16 v[48:51], v[240:243], v[180:183], v[48:51]
	v_mfma_f32_16x16x32_bf16 v[36:39], v[212:215], v[188:191], v[36:39]
	v_mfma_f32_16x16x32_bf16 v[32:35], v[240:243], v[188:191], v[32:35]
	v_mfma_f32_16x16x32_bf16 v[20:23], v[212:215], v[196:199], v[20:23]
	v_mfma_f32_16x16x32_bf16 v[16:19], v[240:243], v[196:199], v[16:19]
	v_mfma_f32_16x16x32_bf16 v[4:7], v[212:215], v[204:207], v[4:7]
	v_mfma_f32_16x16x32_bf16 v[0:3], v[240:243], v[204:207], v[0:3]
	s_setprio 0
	s_add_i32 s43, 0, 0x18000
	v_add_u32_e32 v140, s43, v159
	s_barrier
	ds_read_b128 v[128:131], v140
	ds_read_b128 v[132:135], v140 offset:1024
	ds_read_b128 v[136:139], v140 offset:2048
	ds_read_b128 v[140:143], v140 offset:3072
	s_add_u32 s4, s10, 0xb0000
	s_addc_u32 s5, s11, 0
	s_mov_b32 m0, s21
	v_lshl_add_u64 v[208:209], s[4:5], 0, v[144:145]
	ds_read_b128 v[152:155], v171 offset:32768
	ds_read_b128 v[180:183], v171 offset:33792
	ds_read_b128 v[184:187], v171 offset:34816
	ds_read_b128 v[188:191], v171 offset:35840
	ds_read_b128 v[192:195], v171 offset:36864
	ds_read_b128 v[196:199], v171 offset:37888
	ds_read_b128 v[200:203], v171 offset:38912
	ds_read_b128 v[204:207], v171 offset:39936
	global_load_lds_dwordx4 v[208:209], off
	v_lshl_add_u64 v[208:209], s[4:5], 0, v[146:147]
	s_mov_b32 m0, s22
	s_nop 0
	global_load_lds_dwordx4 v[208:209], off
	s_waitcnt lgkmcnt(8)
	s_barrier
	s_waitcnt lgkmcnt(0)
	s_setprio 1
	s_waitcnt lgkmcnt(0)
	v_mfma_f32_16x16x32_bf16 v[124:127], v[128:131], v[152:155], v[124:127]
	v_mfma_f32_16x16x32_bf16 v[120:123], v[136:139], v[152:155], v[120:123]
	v_mfma_f32_16x16x32_bf16 v[108:111], v[128:131], v[184:187], v[108:111]
	v_mfma_f32_16x16x32_bf16 v[104:107], v[136:139], v[184:187], v[104:107]
	v_mfma_f32_16x16x32_bf16 v[92:95], v[128:131], v[192:195], v[92:95]
	v_mfma_f32_16x16x32_bf16 v[88:91], v[136:139], v[192:195], v[88:91]
	v_mfma_f32_16x16x32_bf16 v[76:79], v[128:131], v[200:203], v[76:79]
	v_mfma_f32_16x16x32_bf16 v[72:75], v[136:139], v[200:203], v[72:75]
	v_mfma_f32_16x16x32_bf16 v[124:127], v[132:135], v[180:183], v[124:127]
	v_mfma_f32_16x16x32_bf16 v[120:123], v[140:143], v[180:183], v[120:123]
	v_mfma_f32_16x16x32_bf16 v[108:111], v[132:135], v[188:191], v[108:111]
	v_mfma_f32_16x16x32_bf16 v[104:107], v[140:143], v[188:191], v[104:107]
	v_mfma_f32_16x16x32_bf16 v[92:95], v[132:135], v[196:199], v[92:95]
	v_mfma_f32_16x16x32_bf16 v[88:91], v[140:143], v[196:199], v[88:91]
	v_mfma_f32_16x16x32_bf16 v[76:79], v[132:135], v[204:207], v[76:79]
	v_mfma_f32_16x16x32_bf16 v[72:75], v[140:143], v[204:207], v[72:75]
	s_setprio 0
	s_barrier
	s_add_i32 s10, 0, 0x1c000
	s_add_i32 s4, s43, s18
	v_add_u32_e32 v166, s10, v159
	v_lshl_add_u64 v[156:157], v[156:157], 0, s[76:77]
	s_mov_b32 m0, s4
	ds_read_b128 v[208:211], v166
	ds_read_b128 v[212:215], v166 offset:1024
	ds_read_b128 v[236:239], v166 offset:2048
	ds_read_b128 v[240:243], v166 offset:3072
	global_load_lds_dwordx4 v[156:157], off
	v_lshl_add_u64 v[156:157], v[172:173], 0, s[76:77]
	s_add_i32 m0, s4, 0x2000
	s_nop 0
	global_load_lds_dwordx4 v[156:157], off
	s_barrier
	s_waitcnt lgkmcnt(0)
	s_setprio 1
	s_waitcnt lgkmcnt(0)
	v_mfma_f32_16x16x32_bf16 v[116:119], v[208:211], v[152:155], v[116:119]
	v_mfma_f32_16x16x32_bf16 v[112:115], v[236:239], v[152:155], v[112:115]
	v_mfma_f32_16x16x32_bf16 v[100:103], v[208:211], v[184:187], v[100:103]
	v_mfma_f32_16x16x32_bf16 v[96:99], v[236:239], v[184:187], v[96:99]
	v_mfma_f32_16x16x32_bf16 v[84:87], v[208:211], v[192:195], v[84:87]
	v_mfma_f32_16x16x32_bf16 v[80:83], v[236:239], v[192:195], v[80:83]
	v_mfma_f32_16x16x32_bf16 v[68:71], v[208:211], v[200:203], v[68:71]
	v_mfma_f32_16x16x32_bf16 v[64:67], v[236:239], v[200:203], v[64:67]
	v_mfma_f32_16x16x32_bf16 v[116:119], v[212:215], v[180:183], v[116:119]
	v_mfma_f32_16x16x32_bf16 v[112:115], v[240:243], v[180:183], v[112:115]
	v_mfma_f32_16x16x32_bf16 v[100:103], v[212:215], v[188:191], v[100:103]
	v_mfma_f32_16x16x32_bf16 v[96:99], v[240:243], v[188:191], v[96:99]
	v_mfma_f32_16x16x32_bf16 v[84:87], v[212:215], v[196:199], v[84:87]
	v_mfma_f32_16x16x32_bf16 v[80:83], v[240:243], v[196:199], v[80:83]
	v_mfma_f32_16x16x32_bf16 v[68:71], v[212:215], v[204:207], v[68:71]
	v_mfma_f32_16x16x32_bf16 v[64:67], v[240:243], v[204:207], v[64:67]
	s_setprio 0
	s_mov_b32 m0, s23
	v_lshl_add_u64 v[156:157], v[174:175], 0, s[76:77]
	s_barrier
	ds_read_b128 v[152:155], v171 offset:49152
	ds_read_b128 v[180:183], v171 offset:50176
	ds_read_b128 v[184:187], v171 offset:51200
	ds_read_b128 v[188:191], v171 offset:52224
	ds_read_b128 v[192:195], v171 offset:53248
	ds_read_b128 v[196:199], v171 offset:54272
	ds_read_b128 v[200:203], v171 offset:55296
	ds_read_b128 v[204:207], v171 offset:56320
	global_load_lds_dwordx4 v[156:157], off
	v_lshl_add_u64 v[156:157], v[244:245], 0, s[76:77]
	s_mov_b32 m0, s24
	s_nop 0
	global_load_lds_dwordx4 v[156:157], off
	s_barrier
; #define PG8_BAR __builtin_amdgcn_s_barrier()
; template <class Epi>
; __device__ __forceinline__ void gemm_phase(PG8_LAS unsigned char* lds, const Gemm g, const Sched& S, const Epi& E) {
;     ...
;             PG8_WAIT_V(6); PG8_BAR; PG8_MMA(1, 1, At, B1); PG8_BAR;
;             PG8_LDB(B0, 1, 0); PG8_SCHED; PG8_LDA(At, 1, 0); PG8_STAGE(PG8_SA(0, 1), a2 + hsA, voffA);
;             PG8_WAIT_L(8); PG8_BAR; PG8_WAIT_L(0); PG8_MMA(0, 0, At, B0); PG8_BAR; PG8_SCHED;
;             PG8_LDB(B1, 1, 1); PG8_STAGE(PG8_SB(1, 0), b3, voffB);
;             PG8_BAR; PG8_WAIT_L(0); PG8_MMA(0, 1, At, B1); PG8_BAR;
;             PG8_LDA(At, 1, 1); PG8_STAGE(PG8_SA(1, 0), a3, voffA);
;             PG8_BAR; PG8_WAIT_L(0); PG8_MMA(1, 0, At, B0); PG8_BAR; PG8_SCHED;
;             PG8_STAGE(PG8_SB(1, 1), b3 + hsB, voffB);
;             PG8_WAIT_V(6); PG8_BAR; PG8_MMA(1, 1, At, B1); PG8_BAR;
;         }
;         E(acc, cur, wr, wc, fr, fq);
;   __device__ __forceinline__ void operator()(const f32x4 (&acc)[2][2][4][2], const pg8::Unit& u, int wr, int wc, int fr, int fq) const {
;     ...
;     if (kind == EPI_RESID) {
;       const float* md0 = modp + ((size_t)layer * 3 + condof(u.pm * 256)) * NMOD + slot * D;
; #pragma unroll
;       for (int bj = 0; bj < 2; ++bj)
; #pragma unroll
;         for (int n = 0; n < 2; ++n) {
;           float4 t = *(const float4*)(md0 + u.pn * 256 + bj * 128 + wc * 32 + n * 16 + fq * 4);
;           gsv[bj][n] = make_float4(t.x * scale, t.y * scale, t.z * scale, t.w * scale);
;         }
;     }
; #pragma unroll
;     for (int ai = 0; ai < 2; ++ai)
; #pragma unroll
;       for (int m = 0; m < 4; ++m) {
;         const int row = u.pm * 256 + ai * 128 + wr * 64 + m * 16 + fr;
;         if (kind == EPI_SWIGLU) {
; #pragma unroll
;           for (int bj = 0; bj < 2; ++bj) {
;             int hc = u.pn * 128 + bj * 64 + wc * 16 + fq * 4;
;             f32x4 g = acc[ai][bj][m][0], up = acc[ai][bj][m][1];
;             uint2 o; o.x = pack2(siluf_(g[0]) * up[0], siluf_(g[1]) * up[1]); o.y = pack2(siluf_(g[2]) * up[2], siluf_(g[3]) * up[3]);
;             *(uint2*)(outb + (size_t)row * ldo + hc) = o;
;           }
;         } else if (kind == EPI_RESID) {
;           float* xb;
;           { int b_ = row >= TPB ? 1 : 0; int u_ = row - b_ * TPB;
;             xb = (u_ < CTX) ? xctx + (size_t)(b_ * CTX + u_) * D : xout + ((size_t)b_ * SEQ + (u_ - CTX)) * D; }
	s_waitcnt lgkmcnt(0)
	s_setprio 1
	s_waitcnt lgkmcnt(0)
	v_mfma_f32_16x16x32_bf16 v[60:63], v[128:131], v[152:155], v[60:63]
	v_mfma_f32_16x16x32_bf16 v[56:59], v[136:139], v[152:155], v[56:59]
	v_mfma_f32_16x16x32_bf16 v[44:47], v[128:131], v[184:187], v[44:47]
	v_mfma_f32_16x16x32_bf16 v[40:43], v[136:139], v[184:187], v[40:43]
	v_mfma_f32_16x16x32_bf16 v[28:31], v[128:131], v[192:195], v[28:31]
	v_mfma_f32_16x16x32_bf16 v[24:27], v[136:139], v[192:195], v[24:27]
	v_mfma_f32_16x16x32_bf16 v[12:15], v[128:131], v[200:203], v[12:15]
	v_mfma_f32_16x16x32_bf16 v[8:11], v[136:139], v[200:203], v[8:11]
	v_mfma_f32_16x16x32_bf16 v[60:63], v[132:135], v[180:183], v[60:63]
	v_mfma_f32_16x16x32_bf16 v[56:59], v[140:143], v[180:183], v[56:59]
	v_mfma_f32_16x16x32_bf16 v[44:47], v[132:135], v[188:191], v[44:47]
	v_mfma_f32_16x16x32_bf16 v[40:43], v[140:143], v[188:191], v[40:43]
	v_mfma_f32_16x16x32_bf16 v[28:31], v[132:135], v[196:199], v[28:31]
	v_mfma_f32_16x16x32_bf16 v[24:27], v[140:143], v[196:199], v[24:27]
	v_mfma_f32_16x16x32_bf16 v[12:15], v[132:135], v[204:207], v[12:15]
	v_mfma_f32_16x16x32_bf16 v[8:11], v[140:143], v[204:207], v[8:11]
	s_setprio 0
	s_barrier
	s_add_u32 s4, s8, 0xb0080
	s_addc_u32 s5, s9, 0
	s_add_i32 s8, s10, s18
	v_lshl_add_u64 v[128:129], s[4:5], 0, v[144:145]
	s_mov_b32 m0, s8
	s_nop 0
	global_load_lds_dwordx4 v[128:129], off
	v_lshl_add_u64 v[128:129], s[4:5], 0, v[146:147]
	s_add_i32 m0, s8, 0x2000
	s_nop 0
	global_load_lds_dwordx4 v[128:129], off
	s_waitcnt vmcnt(6)
	s_barrier
	s_setprio 1
	v_mfma_f32_16x16x32_bf16 v[52:55], v[208:211], v[152:155], v[52:55]
	v_mfma_f32_16x16x32_bf16 v[48:51], v[236:239], v[152:155], v[48:51]
	v_mfma_f32_16x16x32_bf16 v[36:39], v[208:211], v[184:187], v[36:39]
	v_mfma_f32_16x16x32_bf16 v[32:35], v[236:239], v[184:187], v[32:35]
	v_mfma_f32_16x16x32_bf16 v[20:23], v[208:211], v[192:195], v[20:23]
	v_mfma_f32_16x16x32_bf16 v[16:19], v[236:239], v[192:195], v[16:19]
	v_mfma_f32_16x16x32_bf16 v[4:7], v[208:211], v[200:203], v[4:7]
	v_mfma_f32_16x16x32_bf16 v[0:3], v[236:239], v[200:203], v[0:3]
	v_mfma_f32_16x16x32_bf16 v[52:55], v[212:215], v[180:183], v[52:55]
	v_mfma_f32_16x16x32_bf16 v[48:51], v[240:243], v[180:183], v[48:51]
	v_mfma_f32_16x16x32_bf16 v[36:39], v[212:215], v[188:191], v[36:39]
	v_mfma_f32_16x16x32_bf16 v[32:35], v[240:243], v[188:191], v[32:35]
	v_mfma_f32_16x16x32_bf16 v[20:23], v[212:215], v[196:199], v[20:23]
	v_mfma_f32_16x16x32_bf16 v[16:19], v[240:243], v[196:199], v[16:19]
	v_mfma_f32_16x16x32_bf16 v[4:7], v[212:215], v[204:207], v[4:7]
	v_mfma_f32_16x16x32_bf16 v[0:3], v[240:243], v[204:207], v[0:3]
	s_setprio 0
	s_add_i32 s42, s42, 2
	s_add_u32 s2, s2, 0x100
	s_addc_u32 s3, s3, 0
	s_cmp_gt_u32 s42, 41
	s_mov_b64 s[4:5], s[6:7]
	s_barrier
	s_cbranch_scc0 .LBB0_845
	s_lshl_b32 s8, s39, 8
	s_cmp_gt_i32 s39, 32
	s_cselect_b64 s[2:3], -1, 0
	v_cndmask_b32_e64 v128, 0, 1, s[2:3]
	s_and_b64 s[2:3], s[2:3], exec
	s_cselect_b32 s2, 0xffffdf00, 0
	s_add_i32 s2, s2, s8
	s_cmpk_gt_i32 s2, 0xff
	v_readfirstlane_b32 s2, v128
	s_cselect_b32 s2, s2, 2
	s_mul_i32 s3, s17, 3
	s_add_i32 s2, s2, s3
	s_mul_i32 s2, s2, 0x9000
	s_add_u32 s6, s27, s2
	s_addc_u32 s7, s29, 0
	s_lshl_b32 s4, s38, 8
	s_ashr_i32 s5, s4, 31
	s_lshl_b64 s[2:3], s[4:5], 2
	s_add_u32 s2, s6, s2
	s_addc_u32 s3, s7, s3
	s_add_u32 s2, s2, s30
	s_addc_u32 s3, s3, 0
	global_load_dwordx4 v[140:143], v178, s[2:3]
	global_load_dwordx4 v[136:139], v178, s[2:3] offset:64
	global_load_dwordx4 v[132:135], v178, s[2:3] offset:512
	global_load_dwordx4 v[128:131], v178, s[2:3] offset:576
	v_add_u32_e32 v179, s8, v158
	s_movk_i32 s2, 0x20ff
	v_cmp_lt_i32_e32 vcc, s2, v179
	s_nop 1
	v_cndmask_b32_e32 v152, 0, v228, vcc
	v_add_u32_e32 v152, v152, v179
	v_cmp_lt_i32_e64 s[42:43], s81, v152
	s_and_saveexec_b64 s[2:3], s[42:43]
	s_xor_b64 s[2:3], exec, s[2:3]
	v_cndmask_b32_e32 v153, 0, v230, vcc
	s_movk_i32 s5, 0xff00
	v_add3_u32 v166, v152, v153, s5
	v_mov_b64_e32 v[154:155], v[166:167]
	s_or_saveexec_b64 s[6:7], s[2:3]
	v_mov_b64_e32 v[156:157], s[48:49]
	s_xor_b64 exec, exec, s[6:7]
	v_cndmask_b32_e32 v153, 0, v229, vcc
	v_add_u32_e32 v154, v152, v153
	v_ashrrev_i32_e32 v155, 31, v154
	v_mov_b64_e32 v[156:157], s[46:47]
	s_or_b64 exec, exec, s[6:7]
	s_waitcnt vmcnt(0)
	v_pk_mul_f32 v[152:153], v[140:141], 0.5 op_sel_hi:[1,0]
	v_pk_mul_f32 v[140:141], v[136:137], 0.5 op_sel_hi:[1,0]
	v_pk_mul_f32 v[136:137], v[132:133], 0.5 op_sel_hi:[1,0]
	v_pk_mul_f32 v[132:133], v[134:135], 0.5 op_sel_hi:[1,0]
	v_lshlrev_b64 v[134:135], 12, v[154:155]
	v_lshl_add_u64 v[154:155], v[156:157], 0, v[134:135]
	v_cmp_le_u64_e32 vcc, s[48:49], v[154:155]
	v_cmp_gt_u64_e64 s[42:43], s[58:59], v[154:155]
	s_and_b64 vcc, vcc, s[42:43]
	v_subrev_co_u32_e64 v134, s[42:43], s48, v154
	v_mov_b32_e32 v135, s49
	s_nop 0
	v_subb_co_u32_e64 v135, s[42:43], v155, v135, s[42:43]
	v_lshl_add_u64 v[134:135], s[56:57], 0, v[134:135]
	v_cndmask_b32_e32 v156, v154, v134, vcc
	v_or_b32_e32 v134, s4, v160
	v_cndmask_b32_e32 v157, v155, v135, vcc
	v_ashrrev_i32_e32 v135, 31, v134
	v_lshlrev_b64 v[134:135], 2, v[134:135]
	v_lshl_add_u64 v[172:173], v[156:157], 0, v[134:135]
	v_lshl_add_u64 v[174:175], v[154:155], 0, v[134:135]
	global_load_dwordx4 v[154:157], v[172:173], off
	global_load_dwordx4 v[180:183], v[172:173], off offset:64
	global_load_dwordx4 v[184:187], v[172:173], off offset:512
	global_load_dwordx4 v[188:191], v[172:173], off offset:576
	v_pk_mul_f32 v[142:143], v[142:143], 0.5 op_sel_hi:[1,0]
	v_pk_mul_f32 v[138:139], v[138:139], 0.5 op_sel_hi:[1,0]
	v_pk_mul_f32 v[128:129], v[128:129], 0.5 op_sel_hi:[1,0]
	v_pk_mul_f32 v[130:131], v[130:131], 0.5 op_sel_hi:[1,0]
	s_movk_i32 s2, 0x20ff
	s_waitcnt vmcnt(3)
; __device__ __forceinline__ uint32_t pack2(float a, float b) { uint32_t r; asm("v_cvt_pk_bf16_f32 %0, %1, %2" : "=v"(r) : "v"(a), "v"(b)); return r; }
; __device__ __forceinline__ float siluf_(float x) { return x * __builtin_amdgcn_rcpf(1.0f + __expf(-x)); }
;   __device__ __forceinline__ void operator()(const f32x4 (&acc)[2][2][4][2], const pg8::Unit& u, int wr, int wc, int fr, int fq) const {
;     ...
;     for (int ai = 0; ai < 2; ++ai)
; #pragma unroll
;       for (int m = 0; m < 4; ++m) {
;         const int row = u.pm * 256 + ai * 128 + wr * 64 + m * 16 + fr;
;         if (kind == EPI_SWIGLU) {
; #pragma unroll
;           for (int bj = 0; bj < 2; ++bj) {
;             int hc = u.pn * 128 + bj * 64 + wc * 16 + fq * 4;
;             f32x4 g = acc[ai][bj][m][0], up = acc[ai][bj][m][1];
;             uint2 o; o.x = pack2(siluf_(g[0]) * up[0], siluf_(g[1]) * up[1]); o.y = pack2(siluf_(g[2]) * up[2], siluf_(g[3]) * up[3]);
;             *(uint2*)(outb + (size_t)row * ldo + hc) = o;
;           }
;         } else if (kind == EPI_RESID) {
;           float* xb;
;           { int b_ = row >= TPB ? 1 : 0; int u_ = row - b_ * TPB;
;             xb = (u_ < CTX) ? xctx + (size_t)(b_ * CTX + u_) * D : xout + ((size_t)b_ * SEQ + (u_ - CTX)) * D; }
;           const float* xr = (xb >= xout && xb < xout + (size_t)2 * SEQ * D) ? xin + (xb - xout) : xb;
; #pragma unroll
;           for (int bj = 0; bj < 2; ++bj)
; #pragma unroll
;             for (int n = 0; n < 2; ++n) {
;               int cc = u.pn * 256 + bj * 128 + wc * 32 + n * 16 + fq * 4;
;               const float4 gs = gsv[bj][n];
;               float4 xv = *(const float4*)(xr + cc);
;               f32x4 a = acc[ai][bj][m][n];
;               xv.x += gs.x * a[0]; xv.y += gs.y * a[1]; xv.z += gs.z * a[2]; xv.w += gs.w * a[3];
;               *(float4*)(xb + cc) = xv;
	v_pk_fma_f32 v[124:125], v[124:125], v[152:153], v[154:155]
	v_pk_fma_f32 v[126:127], v[126:127], v[142:143], v[156:157]
	global_store_dwordx4 v[174:175], v[124:127], off
	s_waitcnt vmcnt(3)
	v_pk_fma_f32 v[120:121], v[120:121], v[140:141], v[180:181]
	v_pk_fma_f32 v[122:123], v[122:123], v[138:139], v[182:183]
	global_store_dwordx4 v[174:175], v[120:123], off offset:64
	s_waitcnt vmcnt(3)
	v_pk_fma_f32 v[116:117], v[116:117], v[136:137], v[184:185]
	v_pk_fma_f32 v[118:119], v[118:119], v[132:133], v[186:187]
	global_store_dwordx4 v[174:175], v[116:119], off offset:512
	s_waitcnt vmcnt(3)
	v_pk_fma_f32 v[112:113], v[112:113], v[128:129], v[188:189]
	v_pk_fma_f32 v[114:115], v[114:115], v[130:131], v[190:191]
	global_store_dwordx4 v[174:175], v[112:115], off offset:576
	s_nop 1
	v_add_u32_e32 v112, s8, v161
	v_cmp_lt_i32_e32 vcc, s2, v112
	s_nop 1
	v_cndmask_b32_e32 v113, 0, v228, vcc
	v_add_u32_e32 v116, v113, v112
	v_cmp_lt_i32_e64 s[42:43], s81, v116
	s_and_saveexec_b64 s[2:3], s[42:43]
	s_xor_b64 s[2:3], exec, s[2:3]
	v_cndmask_b32_e32 v112, 0, v230, vcc
	s_movk_i32 s4, 0xff00
	v_add3_u32 v166, v116, v112, s4
	v_mov_b64_e32 v[112:113], v[166:167]
	s_or_saveexec_b64 s[4:5], s[2:3]
	v_mov_b64_e32 v[114:115], s[48:49]
	s_xor_b64 exec, exec, s[4:5]
	v_cndmask_b32_e32 v112, 0, v229, vcc
	v_add_u32_e32 v112, v116, v112
	v_ashrrev_i32_e32 v113, 31, v112
	v_mov_b64_e32 v[114:115], s[46:47]
	s_or_b64 exec, exec, s[4:5]
	v_lshlrev_b64 v[112:113], 12, v[112:113]
	v_lshl_add_u64 v[112:113], v[114:115], 0, v[112:113]
	v_cmp_le_u64_e32 vcc, s[48:49], v[112:113]
	v_cmp_gt_u64_e64 s[42:43], s[58:59], v[112:113]
	s_and_b64 vcc, vcc, s[42:43]
	v_subrev_co_u32_e64 v114, s[42:43], s48, v112
	v_mov_b32_e32 v115, s49
	s_nop 0
	v_subb_co_u32_e64 v115, s[42:43], v113, v115, s[42:43]
	v_lshl_add_u64 v[114:115], s[56:57], 0, v[114:115]
	v_cndmask_b32_e32 v115, v113, v115, vcc
	v_cndmask_b32_e32 v114, v112, v114, vcc
	v_lshl_add_u64 v[116:117], v[114:115], 0, v[134:135]
	v_lshl_add_u64 v[118:119], v[112:113], 0, v[134:135]
	global_load_dwordx4 v[112:115], v[116:117], off
	global_load_dwordx4 v[180:183], v[116:117], off offset:64
	global_load_dwordx4 v[184:187], v[116:117], off offset:512
	global_load_dwordx4 v[188:191], v[116:117], off offset:576
	s_movk_i32 s2, 0x20ff
	s_waitcnt vmcnt(3)
	v_pk_fma_f32 v[108:109], v[108:109], v[152:153], v[112:113]
	v_pk_fma_f32 v[110:111], v[110:111], v[142:143], v[114:115]
	global_store_dwordx4 v[118:119], v[108:111], off
	s_waitcnt vmcnt(3)
	v_pk_fma_f32 v[104:105], v[104:105], v[140:141], v[180:181]
	v_pk_fma_f32 v[106:107], v[106:107], v[138:139], v[182:183]
	global_store_dwordx4 v[118:119], v[104:107], off offset:64
	s_waitcnt vmcnt(3)
	v_pk_fma_f32 v[100:101], v[100:101], v[136:137], v[184:185]
	v_pk_fma_f32 v[102:103], v[102:103], v[132:133], v[186:187]
	global_store_dwordx4 v[118:119], v[100:103], off offset:512
	s_waitcnt vmcnt(3)
	v_pk_fma_f32 v[96:97], v[96:97], v[128:129], v[188:189]
	v_pk_fma_f32 v[98:99], v[98:99], v[130:131], v[190:191]
	global_store_dwordx4 v[118:119], v[96:99], off offset:576
	s_nop 1
	v_add_u32_e32 v96, s8, v162
	v_cmp_lt_i32_e32 vcc, s2, v96
	s_nop 1
	v_cndmask_b32_e32 v97, 0, v228, vcc
	v_add_u32_e32 v100, v97, v96
	v_cmp_lt_i32_e64 s[42:43], s81, v100
	s_and_saveexec_b64 s[2:3], s[42:43]
	s_xor_b64 s[2:3], exec, s[2:3]
	v_cndmask_b32_e32 v96, 0, v230, vcc
	s_movk_i32 s4, 0xff00
	v_add3_u32 v166, v100, v96, s4
	v_mov_b64_e32 v[96:97], v[166:167]
	s_or_saveexec_b64 s[4:5], s[2:3]
	v_mov_b64_e32 v[98:99], s[48:49]
	s_xor_b64 exec, exec, s[4:5]
	v_cndmask_b32_e32 v96, 0, v229, vcc
	v_add_u32_e32 v96, v100, v96
	v_ashrrev_i32_e32 v97, 31, v96
	v_mov_b64_e32 v[98:99], s[46:47]
	s_or_b64 exec, exec, s[4:5]
	v_lshlrev_b64 v[96:97], 12, v[96:97]
	v_lshl_add_u64 v[96:97], v[98:99], 0, v[96:97]
	v_cmp_le_u64_e32 vcc, s[48:49], v[96:97]
	v_cmp_gt_u64_e64 s[42:43], s[58:59], v[96:97]
	s_and_b64 vcc, vcc, s[42:43]
	v_subrev_co_u32_e64 v98, s[42:43], s48, v96
	v_mov_b32_e32 v99, s49
	s_nop 0
	v_subb_co_u32_e64 v99, s[42:43], v97, v99, s[42:43]
	v_lshl_add_u64 v[98:99], s[56:57], 0, v[98:99]
	v_cndmask_b32_e32 v99, v97, v99, vcc
	v_cndmask_b32_e32 v98, v96, v98, vcc
	v_lshl_add_u64 v[100:101], v[98:99], 0, v[134:135]
	v_lshl_add_u64 v[102:103], v[96:97], 0, v[134:135]
	global_load_dwordx4 v[96:99], v[100:101], off
	global_load_dwordx4 v[180:183], v[100:101], off offset:64
	global_load_dwordx4 v[184:187], v[100:101], off offset:512
	global_load_dwordx4 v[188:191], v[100:101], off offset:576
	s_movk_i32 s2, 0x20ff
	s_waitcnt vmcnt(3)
	v_pk_fma_f32 v[92:93], v[92:93], v[152:153], v[96:97]
	v_pk_fma_f32 v[94:95], v[94:95], v[142:143], v[98:99]
	global_store_dwordx4 v[102:103], v[92:95], off
	s_waitcnt vmcnt(3)
	v_pk_fma_f32 v[88:89], v[88:89], v[140:141], v[180:181]
	v_pk_fma_f32 v[90:91], v[90:91], v[138:139], v[182:183]
	global_store_dwordx4 v[102:103], v[88:91], off offset:64
	s_waitcnt vmcnt(3)
	v_pk_fma_f32 v[84:85], v[84:85], v[136:137], v[184:185]
	v_pk_fma_f32 v[86:87], v[86:87], v[132:133], v[186:187]
	global_store_dwordx4 v[102:103], v[84:87], off offset:512
	s_waitcnt vmcnt(3)
; __device__ __forceinline__ uint32_t pack2(float a, float b) { uint32_t r; asm("v_cvt_pk_bf16_f32 %0, %1, %2" : "=v"(r) : "v"(a), "v"(b)); return r; }
; __device__ __forceinline__ float siluf_(float x) { return x * __builtin_amdgcn_rcpf(1.0f + __expf(-x)); }
;   __device__ __forceinline__ void operator()(const f32x4 (&acc)[2][2][4][2], const pg8::Unit& u, int wr, int wc, int fr, int fq) const {
;     ...
;     for (int ai = 0; ai < 2; ++ai)
; #pragma unroll
;       for (int m = 0; m < 4; ++m) {
;         const int row = u.pm * 256 + ai * 128 + wr * 64 + m * 16 + fr;
;         if (kind == EPI_SWIGLU) {
; #pragma unroll
;           for (int bj = 0; bj < 2; ++bj) {
;             int hc = u.pn * 128 + bj * 64 + wc * 16 + fq * 4;
;             f32x4 g = acc[ai][bj][m][0], up = acc[ai][bj][m][1];
;             uint2 o; o.x = pack2(siluf_(g[0]) * up[0], siluf_(g[1]) * up[1]); o.y = pack2(siluf_(g[2]) * up[2], siluf_(g[3]) * up[3]);
;             *(uint2*)(outb + (size_t)row * ldo + hc) = o;
;           }
;         } else if (kind == EPI_RESID) {
;           float* xb;
;           { int b_ = row >= TPB ? 1 : 0; int u_ = row - b_ * TPB;
;             xb = (u_ < CTX) ? xctx + (size_t)(b_ * CTX + u_) * D : xout + ((size_t)b_ * SEQ + (u_ - CTX)) * D; }
;           const float* xr = (xb >= xout && xb < xout + (size_t)2 * SEQ * D) ? xin + (xb - xout) : xb;
; #pragma unroll
;           for (int bj = 0; bj < 2; ++bj)
; #pragma unroll
;             for (int n = 0; n < 2; ++n) {
;               int cc = u.pn * 256 + bj * 128 + wc * 32 + n * 16 + fq * 4;
;               const float4 gs = gsv[bj][n];
;               float4 xv = *(const float4*)(xr + cc);
;               f32x4 a = acc[ai][bj][m][n];
;               xv.x += gs.x * a[0]; xv.y += gs.y * a[1]; xv.z += gs.z * a[2]; xv.w += gs.w * a[3];
;               *(float4*)(xb + cc) = xv;
	v_pk_fma_f32 v[80:81], v[80:81], v[128:129], v[188:189]
	v_pk_fma_f32 v[82:83], v[82:83], v[130:131], v[190:191]
	global_store_dwordx4 v[102:103], v[80:83], off offset:576
	s_nop 1
	v_add_u32_e32 v80, s8, v163
	v_cmp_lt_i32_e32 vcc, s2, v80
	s_nop 1
	v_cndmask_b32_e32 v81, 0, v228, vcc
	v_add_u32_e32 v84, v81, v80
	v_cmp_lt_i32_e64 s[42:43], s81, v84
	s_and_saveexec_b64 s[2:3], s[42:43]
	s_xor_b64 s[2:3], exec, s[2:3]
	v_cndmask_b32_e32 v80, 0, v230, vcc
	s_movk_i32 s4, 0xff00
	v_add3_u32 v166, v84, v80, s4
	v_mov_b64_e32 v[80:81], v[166:167]
	s_or_saveexec_b64 s[4:5], s[2:3]
	v_mov_b64_e32 v[82:83], s[48:49]
	s_xor_b64 exec, exec, s[4:5]
	v_cndmask_b32_e32 v80, 0, v229, vcc
	v_add_u32_e32 v80, v84, v80
	v_ashrrev_i32_e32 v81, 31, v80
	v_mov_b64_e32 v[82:83], s[46:47]
	s_or_b64 exec, exec, s[4:5]
	v_lshlrev_b64 v[80:81], 12, v[80:81]
	v_lshl_add_u64 v[80:81], v[82:83], 0, v[80:81]
	v_cmp_le_u64_e32 vcc, s[48:49], v[80:81]
	v_cmp_gt_u64_e64 s[42:43], s[58:59], v[80:81]
	s_and_b64 vcc, vcc, s[42:43]
	v_subrev_co_u32_e64 v82, s[42:43], s48, v80
	v_mov_b32_e32 v83, s49
	s_nop 0
	v_subb_co_u32_e64 v83, s[42:43], v81, v83, s[42:43]
	v_lshl_add_u64 v[82:83], s[56:57], 0, v[82:83]
	v_cndmask_b32_e32 v83, v81, v83, vcc
	v_cndmask_b32_e32 v82, v80, v82, vcc
	v_lshl_add_u64 v[84:85], v[82:83], 0, v[134:135]
	v_lshl_add_u64 v[86:87], v[80:81], 0, v[134:135]
	global_load_dwordx4 v[80:83], v[84:85], off
	global_load_dwordx4 v[180:183], v[84:85], off offset:64
	global_load_dwordx4 v[184:187], v[84:85], off offset:512
	global_load_dwordx4 v[188:191], v[84:85], off offset:576
	s_movk_i32 s2, 0x20ff
	s_waitcnt vmcnt(3)
	v_pk_fma_f32 v[76:77], v[76:77], v[152:153], v[80:81]
	v_pk_fma_f32 v[78:79], v[78:79], v[142:143], v[82:83]
	global_store_dwordx4 v[86:87], v[76:79], off
	s_waitcnt vmcnt(3)
	v_pk_fma_f32 v[72:73], v[72:73], v[140:141], v[180:181]
	v_pk_fma_f32 v[74:75], v[74:75], v[138:139], v[182:183]
	global_store_dwordx4 v[86:87], v[72:75], off offset:64
	s_waitcnt vmcnt(3)
	v_pk_fma_f32 v[68:69], v[68:69], v[136:137], v[184:185]
	v_pk_fma_f32 v[70:71], v[70:71], v[132:133], v[186:187]
	global_store_dwordx4 v[86:87], v[68:71], off offset:512
	s_waitcnt vmcnt(3)
	v_pk_fma_f32 v[64:65], v[64:65], v[128:129], v[188:189]
	v_pk_fma_f32 v[66:67], v[66:67], v[130:131], v[190:191]
	global_store_dwordx4 v[86:87], v[64:67], off offset:576
	s_nop 1
	v_add_u32_e32 v64, 0x80, v179
	v_cmp_lt_i32_e32 vcc, s2, v64
	s_nop 1
	v_cndmask_b32_e32 v65, 0, v228, vcc
	v_add_u32_e32 v68, v65, v64
	v_cmp_lt_i32_e64 s[42:43], s81, v68
	s_and_saveexec_b64 s[2:3], s[42:43]
	s_xor_b64 s[2:3], exec, s[2:3]
	v_cndmask_b32_e32 v64, 0, v230, vcc
	s_movk_i32 s4, 0xff00
	v_add3_u32 v166, v68, v64, s4
	v_mov_b64_e32 v[64:65], v[166:167]
	s_or_saveexec_b64 s[4:5], s[2:3]
	v_mov_b64_e32 v[66:67], s[48:49]
	s_xor_b64 exec, exec, s[4:5]
	v_cndmask_b32_e32 v64, 0, v229, vcc
	v_add_u32_e32 v64, v68, v64
	v_ashrrev_i32_e32 v65, 31, v64
	v_mov_b64_e32 v[66:67], s[46:47]
	s_or_b64 exec, exec, s[4:5]
	v_lshlrev_b64 v[64:65], 12, v[64:65]
	v_lshl_add_u64 v[64:65], v[66:67], 0, v[64:65]
	v_cmp_le_u64_e32 vcc, s[48:49], v[64:65]
	v_cmp_gt_u64_e64 s[42:43], s[58:59], v[64:65]
	s_and_b64 vcc, vcc, s[42:43]
	v_subrev_co_u32_e64 v66, s[42:43], s48, v64
	v_mov_b32_e32 v67, s49
	s_nop 0
	v_subb_co_u32_e64 v67, s[42:43], v65, v67, s[42:43]
	v_lshl_add_u64 v[66:67], s[56:57], 0, v[66:67]
	v_cndmask_b32_e32 v67, v65, v67, vcc
	v_cndmask_b32_e32 v66, v64, v66, vcc
	v_lshl_add_u64 v[68:69], v[66:67], 0, v[134:135]
	v_lshl_add_u64 v[70:71], v[64:65], 0, v[134:135]
	global_load_dwordx4 v[64:67], v[68:69], off
	global_load_dwordx4 v[180:183], v[68:69], off offset:64
	global_load_dwordx4 v[184:187], v[68:69], off offset:512
	global_load_dwordx4 v[188:191], v[68:69], off offset:576
	s_movk_i32 s2, 0x20ff
	s_waitcnt vmcnt(3)
	v_pk_fma_f32 v[60:61], v[60:61], v[152:153], v[64:65]
	v_pk_fma_f32 v[62:63], v[62:63], v[142:143], v[66:67]
	global_store_dwordx4 v[70:71], v[60:63], off
	s_waitcnt vmcnt(3)
	v_pk_fma_f32 v[56:57], v[56:57], v[140:141], v[180:181]
	v_pk_fma_f32 v[58:59], v[58:59], v[138:139], v[182:183]
	global_store_dwordx4 v[70:71], v[56:59], off offset:64
	s_waitcnt vmcnt(3)
	v_pk_fma_f32 v[52:53], v[52:53], v[136:137], v[184:185]
	v_pk_fma_f32 v[54:55], v[54:55], v[132:133], v[186:187]
	global_store_dwordx4 v[70:71], v[52:55], off offset:512
	s_waitcnt vmcnt(3)
; __device__ __forceinline__ uint32_t pack2(float a, float b) { uint32_t r; asm("v_cvt_pk_bf16_f32 %0, %1, %2" : "=v"(r) : "v"(a), "v"(b)); return r; }
; __device__ __forceinline__ float siluf_(float x) { return x * __builtin_amdgcn_rcpf(1.0f + __expf(-x)); }
;   __device__ __forceinline__ void operator()(const f32x4 (&acc)[2][2][4][2], const pg8::Unit& u, int wr, int wc, int fr, int fq) const {
;     ...
;     for (int ai = 0; ai < 2; ++ai)
; #pragma unroll
;       for (int m = 0; m < 4; ++m) {
;         const int row = u.pm * 256 + ai * 128 + wr * 64 + m * 16 + fr;
;         if (kind == EPI_SWIGLU) {
; #pragma unroll
;           for (int bj = 0; bj < 2; ++bj) {
;             int hc = u.pn * 128 + bj * 64 + wc * 16 + fq * 4;
;             f32x4 g = acc[ai][bj][m][0], up = acc[ai][bj][m][1];
;             uint2 o; o.x = pack2(siluf_(g[0]) * up[0], siluf_(g[1]) * up[1]); o.y = pack2(siluf_(g[2]) * up[2], siluf_(g[3]) * up[3]);
;             *(uint2*)(outb + (size_t)row * ldo + hc) = o;
;           }
;         } else if (kind == EPI_RESID) {
;           float* xb;
;           { int b_ = row >= TPB ? 1 : 0; int u_ = row - b_ * TPB;
;             xb = (u_ < CTX) ? xctx + (size_t)(b_ * CTX + u_) * D : xout + ((size_t)b_ * SEQ + (u_ - CTX)) * D; }
;           const float* xr = (xb >= xout && xb < xout + (size_t)2 * SEQ * D) ? xin + (xb - xout) : xb;
; #pragma unroll
;           for (int bj = 0; bj < 2; ++bj)
; #pragma unroll
;             for (int n = 0; n < 2; ++n) {
;               int cc = u.pn * 256 + bj * 128 + wc * 32 + n * 16 + fq * 4;
;               const float4 gs = gsv[bj][n];
;               float4 xv = *(const float4*)(xr + cc);
;               f32x4 a = acc[ai][bj][m][n];
;               xv.x += gs.x * a[0]; xv.y += gs.y * a[1]; xv.z += gs.z * a[2]; xv.w += gs.w * a[3];
;               *(float4*)(xb + cc) = xv;
	v_pk_fma_f32 v[48:49], v[48:49], v[128:129], v[188:189]
	v_pk_fma_f32 v[50:51], v[50:51], v[130:131], v[190:191]
	global_store_dwordx4 v[70:71], v[48:51], off offset:576
	s_nop 1
	v_add_u32_e32 v48, 0x90, v179
	v_cmp_lt_i32_e32 vcc, s2, v48
	s_nop 1
	v_cndmask_b32_e32 v49, 0, v228, vcc
	v_add_u32_e32 v52, v49, v48
	v_cmp_lt_i32_e64 s[42:43], s81, v52
	s_and_saveexec_b64 s[2:3], s[42:43]
	s_xor_b64 s[2:3], exec, s[2:3]
	v_cndmask_b32_e32 v48, 0, v230, vcc
	s_movk_i32 s4, 0xff00
	v_add3_u32 v166, v52, v48, s4
	v_mov_b64_e32 v[48:49], v[166:167]
	s_or_saveexec_b64 s[4:5], s[2:3]
	v_mov_b64_e32 v[50:51], s[48:49]
	s_xor_b64 exec, exec, s[4:5]
	v_cndmask_b32_e32 v48, 0, v229, vcc
	v_add_u32_e32 v48, v52, v48
	v_ashrrev_i32_e32 v49, 31, v48
	v_mov_b64_e32 v[50:51], s[46:47]
	s_or_b64 exec, exec, s[4:5]
	v_lshlrev_b64 v[48:49], 12, v[48:49]
	v_lshl_add_u64 v[48:49], v[50:51], 0, v[48:49]
	v_cmp_le_u64_e32 vcc, s[48:49], v[48:49]
	v_cmp_gt_u64_e64 s[42:43], s[58:59], v[48:49]
	s_and_b64 vcc, vcc, s[42:43]
	v_subrev_co_u32_e64 v50, s[42:43], s48, v48
	v_mov_b32_e32 v51, s49
	s_nop 0
	v_subb_co_u32_e64 v51, s[42:43], v49, v51, s[42:43]
	v_lshl_add_u64 v[50:51], s[56:57], 0, v[50:51]
	v_cndmask_b32_e32 v51, v49, v51, vcc
	v_cndmask_b32_e32 v50, v48, v50, vcc
	v_lshl_add_u64 v[52:53], v[50:51], 0, v[134:135]
	v_lshl_add_u64 v[54:55], v[48:49], 0, v[134:135]
	global_load_dwordx4 v[48:51], v[52:53], off
	global_load_dwordx4 v[180:183], v[52:53], off offset:64
	global_load_dwordx4 v[184:187], v[52:53], off offset:512
	global_load_dwordx4 v[188:191], v[52:53], off offset:576
	s_movk_i32 s2, 0x20ff
	s_waitcnt vmcnt(3)
	v_pk_fma_f32 v[44:45], v[44:45], v[152:153], v[48:49]
	v_pk_fma_f32 v[46:47], v[46:47], v[142:143], v[50:51]
	global_store_dwordx4 v[54:55], v[44:47], off
	s_waitcnt vmcnt(3)
	v_pk_fma_f32 v[40:41], v[40:41], v[140:141], v[180:181]
	v_pk_fma_f32 v[42:43], v[42:43], v[138:139], v[182:183]
	global_store_dwordx4 v[54:55], v[40:43], off offset:64
	s_waitcnt vmcnt(3)
	v_pk_fma_f32 v[36:37], v[36:37], v[136:137], v[184:185]
	v_pk_fma_f32 v[38:39], v[38:39], v[132:133], v[186:187]
	global_store_dwordx4 v[54:55], v[36:39], off offset:512
	s_waitcnt vmcnt(3)
	v_pk_fma_f32 v[32:33], v[32:33], v[128:129], v[188:189]
	v_pk_fma_f32 v[34:35], v[34:35], v[130:131], v[190:191]
	global_store_dwordx4 v[54:55], v[32:35], off offset:576
	s_nop 1
	v_add_u32_e32 v32, 0xa0, v179
	v_cmp_lt_i32_e32 vcc, s2, v32
	s_nop 1
	v_cndmask_b32_e32 v33, 0, v228, vcc
	v_add_u32_e32 v36, v33, v32
	v_cmp_lt_i32_e64 s[42:43], s81, v36
	s_and_saveexec_b64 s[2:3], s[42:43]
	s_xor_b64 s[2:3], exec, s[2:3]
	v_cndmask_b32_e32 v32, 0, v230, vcc
	s_movk_i32 s4, 0xff00
	v_add3_u32 v166, v36, v32, s4
	v_mov_b64_e32 v[32:33], v[166:167]
	s_or_saveexec_b64 s[4:5], s[2:3]
	v_mov_b64_e32 v[34:35], s[48:49]
	s_xor_b64 exec, exec, s[4:5]
	v_cndmask_b32_e32 v32, 0, v229, vcc
	v_add_u32_e32 v32, v36, v32
	v_ashrrev_i32_e32 v33, 31, v32
	v_mov_b64_e32 v[34:35], s[46:47]
	s_or_b64 exec, exec, s[4:5]
	v_lshlrev_b64 v[32:33], 12, v[32:33]
	v_lshl_add_u64 v[32:33], v[34:35], 0, v[32:33]
	v_cmp_le_u64_e32 vcc, s[48:49], v[32:33]
	v_cmp_gt_u64_e64 s[42:43], s[58:59], v[32:33]
	s_and_b64 vcc, vcc, s[42:43]
	v_subrev_co_u32_e64 v34, s[42:43], s48, v32
	v_mov_b32_e32 v35, s49
	s_nop 0
	v_subb_co_u32_e64 v35, s[42:43], v33, v35, s[42:43]
	v_lshl_add_u64 v[34:35], s[56:57], 0, v[34:35]
	v_cndmask_b32_e32 v35, v33, v35, vcc
	v_cndmask_b32_e32 v34, v32, v34, vcc
	v_lshl_add_u64 v[36:37], v[34:35], 0, v[134:135]
	v_lshl_add_u64 v[38:39], v[32:33], 0, v[134:135]
	global_load_dwordx4 v[32:35], v[36:37], off
	global_load_dwordx4 v[180:183], v[36:37], off offset:64
	global_load_dwordx4 v[184:187], v[36:37], off offset:512
	global_load_dwordx4 v[188:191], v[36:37], off offset:576
	s_movk_i32 s2, 0x20ff
	s_waitcnt vmcnt(3)
	v_pk_fma_f32 v[28:29], v[28:29], v[152:153], v[32:33]
	v_pk_fma_f32 v[30:31], v[30:31], v[142:143], v[34:35]
	global_store_dwordx4 v[38:39], v[28:31], off
	s_waitcnt vmcnt(3)
	v_pk_fma_f32 v[24:25], v[24:25], v[140:141], v[180:181]
	v_pk_fma_f32 v[26:27], v[26:27], v[138:139], v[182:183]
	global_store_dwordx4 v[38:39], v[24:27], off offset:64
	s_waitcnt vmcnt(3)
	v_pk_fma_f32 v[20:21], v[20:21], v[136:137], v[184:185]
	v_pk_fma_f32 v[22:23], v[22:23], v[132:133], v[186:187]
	global_store_dwordx4 v[38:39], v[20:23], off offset:512
	s_waitcnt vmcnt(3)
	v_pk_fma_f32 v[16:17], v[16:17], v[128:129], v[188:189]
	v_pk_fma_f32 v[18:19], v[18:19], v[130:131], v[190:191]
	global_store_dwordx4 v[38:39], v[16:19], off offset:576
	s_nop 1
	v_add_u32_e32 v16, 0xb0, v179
	v_cmp_lt_i32_e32 vcc, s2, v16
	s_nop 1
	v_cndmask_b32_e32 v17, 0, v228, vcc
	v_add_u32_e32 v20, v17, v16
	v_cmp_lt_i32_e64 s[42:43], s81, v20
	s_and_saveexec_b64 s[2:3], s[42:43]
	s_xor_b64 s[2:3], exec, s[2:3]
	v_cndmask_b32_e32 v16, 0, v230, vcc
	s_movk_i32 s4, 0xff00
	v_add3_u32 v166, v20, v16, s4
	v_mov_b64_e32 v[16:17], v[166:167]
	s_or_saveexec_b64 s[4:5], s[2:3]
	v_mov_b64_e32 v[18:19], s[48:49]
	s_xor_b64 exec, exec, s[4:5]
	s_cbranch_execz .LBB0_833
	v_cndmask_b32_e32 v16, 0, v229, vcc
	v_add_u32_e32 v16, v20, v16
	v_ashrrev_i32_e32 v17, 31, v16
	v_mov_b64_e32 v[18:19], s[46:47]
	s_branch .LBB0_833
